# 7.11 back-edge rotation on 7 GEMM K loops: counter/pointer updates, next-iteration selects and exit test moved in front of the loop-back barrier
# baseline (speedup 1.0000x reference)
.LBB0_247:
	s_ashr_i32 s45, s44, 31
	s_lshl_b64 s[20:21], s[44:45], 19
	s_add_u32 s50, s16, s20
	s_addc_u32 s51, s17, s21
	s_and_b64 s[20:21], s[48:49], exec
	s_cselect_b32 s33, s51, s55
	s_cselect_b32 s39, s50, s54
	s_ashr_i32 s47, s46, 31
	s_lshl_b64 s[20:21], s[46:47], 19
	v_readlane_b32 s26, v255, 29
	v_readlane_b32 s27, v255, 30
	s_add_u32 s52, s26, s20
	s_addc_u32 s53, s27, s21
	s_and_b64 s[20:21], s[48:49], exec
	s_cselect_b32 s45, s53, s57
	s_cselect_b32 s47, s52, s56
	s_add_u32 s54, s54, 0x40080
	s_addc_u32 s55, s55, 0
	s_add_u32 s66, s56, 0x100
	v_mov_b32_e32 v0, 0
	s_addc_u32 s67, s57, 0
	s_mov_b32 s68, -2
	v_mov_b32_e32 v1, v0
	v_mov_b32_e32 v2, v0
	v_mov_b32_e32 v3, v0
	v_mov_b32_e32 v4, v0
	v_mov_b32_e32 v5, v0
	v_mov_b32_e32 v6, v0
	v_mov_b32_e32 v7, v0
	s_waitcnt vmcnt(0)
	v_mov_b32_e32 v16, v0
	v_mov_b32_e32 v17, v0
	v_mov_b32_e32 v18, v0
	v_mov_b32_e32 v19, v0
	v_mov_b32_e32 v20, v0
	v_mov_b32_e32 v21, v0
	v_mov_b32_e32 v22, v0
	v_mov_b32_e32 v23, v0
	v_mov_b32_e32 v32, v0
	v_mov_b32_e32 v33, v0
	v_mov_b32_e32 v34, v0
	v_mov_b32_e32 v35, v0
	v_mov_b32_e32 v36, v0
	v_mov_b32_e32 v37, v0
	v_mov_b32_e32 v38, v0
	v_mov_b32_e32 v39, v0
	v_mov_b32_e32 v50, v0
	v_mov_b32_e32 v51, v0
	v_mov_b32_e32 v52, v0
	v_mov_b32_e32 v53, v0
	v_mov_b32_e32 v54, v0
	v_mov_b32_e32 v55, v0
	v_mov_b32_e32 v56, v0
	v_mov_b32_e32 v57, v0
	v_mov_b32_e32 v8, v0
	v_mov_b32_e32 v9, v0
	v_mov_b32_e32 v10, v0
	v_mov_b32_e32 v11, v0
	v_mov_b32_e32 v12, v0
	v_mov_b32_e32 v13, v0
	v_mov_b32_e32 v14, v0
	v_mov_b32_e32 v15, v0
	v_mov_b32_e32 v24, v0
	v_mov_b32_e32 v25, v0
	v_mov_b32_e32 v26, v0
	v_mov_b32_e32 v27, v0
	v_mov_b32_e32 v28, v0
	v_mov_b32_e32 v29, v0
	v_mov_b32_e32 v30, v0
	v_mov_b32_e32 v31, v0
	v_mov_b32_e32 v40, v0
	v_mov_b32_e32 v41, v0
	v_mov_b32_e32 v42, v0
	v_mov_b32_e32 v43, v0
	v_mov_b32_e32 v44, v0
	v_mov_b32_e32 v45, v0
	v_mov_b32_e32 v46, v0
	v_mov_b32_e32 v47, v0
	v_mov_b32_e32 v58, v0
	v_mov_b32_e32 v59, v0
	v_mov_b32_e32 v60, v0
	v_mov_b32_e32 v61, v0
	v_mov_b32_e32 v62, v0
	v_mov_b32_e32 v63, v0
	v_mov_b32_e32 v64, v0
	v_mov_b32_e32 v65, v0
	v_mov_b32_e32 v66, v0
	v_mov_b32_e32 v67, v0
	v_mov_b32_e32 v68, v0
	v_mov_b32_e32 v69, v0
	v_mov_b32_e32 v70, v0
	v_mov_b32_e32 v71, v0
	v_mov_b32_e32 v72, v0
	v_mov_b32_e32 v73, v0
	v_mov_b32_e32 v82, v0
	v_mov_b32_e32 v83, v0
	v_mov_b32_e32 v84, v0
	v_mov_b32_e32 v85, v0
	v_mov_b32_e32 v86, v0
	v_mov_b32_e32 v87, v0
	v_mov_b32_e32 v88, v0
	v_mov_b32_e32 v89, v0
	v_mov_b32_e32 v98, v0
	v_mov_b32_e32 v99, v0
	v_mov_b32_e32 v100, v0
	v_mov_b32_e32 v101, v0
	v_mov_b32_e32 v102, v0
	v_mov_b32_e32 v103, v0
	v_mov_b32_e32 v104, v0
	v_mov_b32_e32 v105, v0
	v_mov_b32_e32 v114, v0
	v_mov_b32_e32 v115, v0
	v_mov_b32_e32 v116, v0
	v_mov_b32_e32 v117, v0
	v_mov_b32_e32 v118, v0
	v_mov_b32_e32 v119, v0
	v_mov_b32_e32 v120, v0
	v_mov_b32_e32 v121, v0
	v_mov_b32_e32 v74, v0
	v_mov_b32_e32 v75, v0
	v_mov_b32_e32 v76, v0
	v_mov_b32_e32 v77, v0
	v_mov_b32_e32 v78, v0
	v_mov_b32_e32 v79, v0
	v_mov_b32_e32 v80, v0
	v_mov_b32_e32 v81, v0
	v_mov_b32_e32 v90, v0
	v_mov_b32_e32 v91, v0
	v_mov_b32_e32 v92, v0
	v_mov_b32_e32 v93, v0
	v_mov_b32_e32 v94, v0
	v_mov_b32_e32 v95, v0
	v_mov_b32_e32 v96, v0
	v_mov_b32_e32 v97, v0
	v_mov_b32_e32 v106, v0
	v_mov_b32_e32 v107, v0
	v_mov_b32_e32 v108, v0
	v_mov_b32_e32 v109, v0
	v_mov_b32_e32 v110, v0
	v_mov_b32_e32 v111, v0
	v_mov_b32_e32 v112, v0
	v_mov_b32_e32 v113, v0
	v_mov_b32_e32 v122, v0
	v_mov_b32_e32 v123, v0
	v_mov_b32_e32 v124, v0
	v_mov_b32_e32 v125, v0
	v_mov_b32_e32 v126, v0
	v_mov_b32_e32 v127, v0
	v_mov_b32_e32 v128, v0
	v_mov_b32_e32 v129, v0
	s_add_u32 s6, s54, 0xfffc0080
	s_addc_u32 s20, s55, -1
	s_cmp_eq_u32 s68, 12
	s_cselect_b32 s59, s33, s20
	s_cselect_b32 s58, s39, s6
	s_cselect_b32 s57, s45, s67
	s_cselect_b32 s56, s47, s66
.LBB0_248:
	s_add_i32 s21, 0, 0x10000
	v_add_u32_e32 v48, s21, v173
	s_add_i32 s6, 0, 0x14000
	ds_read_b128 v[138:141], v48
	ds_read_b128 v[142:145], v48 offset:1024
	ds_read_b128 v[146:149], v48 offset:2048
	ds_read_b128 v[150:153], v48 offset:3072
	v_add_u32_e32 v48, s6, v173
	ds_read_b128 v[156:159], v48
	ds_read_b128 v[160:163], v48 offset:1024
	ds_read_b128 v[164:167], v48 offset:2048
	ds_read_b128 v[168:171], v48 offset:3072
	v_lshl_add_u64 v[202:203], s[54:55], 0, v[134:135]
	s_add_i32 m0, s60, 0xc000
	ds_read_b128 v[178:181], v176
	ds_read_b128 v[182:185], v176 offset:1024
	ds_read_b128 v[186:189], v176 offset:2048
	ds_read_b128 v[190:193], v176 offset:3072
	ds_read_b128 v[194:197], v176 offset:4096
	ds_read_b128 v[198:201], v176 offset:5120
	ds_read_b128 v[216:219], v176 offset:6144
	ds_read_b128 v[220:223], v176 offset:7168
	global_load_lds_dwordx4 v[202:203], off
	v_lshl_add_u64 v[202:203], s[54:55], 0, v[136:137]
	s_add_i32 m0, s60, 0xe000
	s_nop 0
	global_load_lds_dwordx4 v[202:203], off
	s_waitcnt vmcnt(8)
	s_waitcnt lgkmcnt(0)
	s_barrier
	s_setprio 1
	v_mfma_f32_16x16x32_bf16 v[126:129], v[138:141], v[178:181], v[126:129]
	v_mfma_f32_16x16x32_bf16 v[122:125], v[146:149], v[178:181], v[122:125]
	v_mfma_f32_16x16x32_bf16 v[110:113], v[138:141], v[186:189], v[110:113]
	v_mfma_f32_16x16x32_bf16 v[106:109], v[146:149], v[186:189], v[106:109]
	v_mfma_f32_16x16x32_bf16 v[94:97], v[138:141], v[194:197], v[94:97]
	v_mfma_f32_16x16x32_bf16 v[90:93], v[146:149], v[194:197], v[90:93]
	v_mfma_f32_16x16x32_bf16 v[78:81], v[138:141], v[216:219], v[78:81]
	v_mfma_f32_16x16x32_bf16 v[74:77], v[146:149], v[216:219], v[74:77]
	v_mfma_f32_16x16x32_bf16 v[126:129], v[142:145], v[182:185], v[126:129]
	v_mfma_f32_16x16x32_bf16 v[122:125], v[150:153], v[182:185], v[122:125]
	v_mfma_f32_16x16x32_bf16 v[110:113], v[142:145], v[190:193], v[110:113]
	v_mfma_f32_16x16x32_bf16 v[106:109], v[150:153], v[190:193], v[106:109]
	v_mfma_f32_16x16x32_bf16 v[94:97], v[142:145], v[198:201], v[94:97]
	v_mfma_f32_16x16x32_bf16 v[90:93], v[150:153], v[198:201], v[90:93]
	v_mfma_f32_16x16x32_bf16 v[78:81], v[142:145], v[220:223], v[78:81]
	v_mfma_f32_16x16x32_bf16 v[74:77], v[150:153], v[220:223], v[74:77]
	v_mfma_f32_16x16x32_bf16 v[118:121], v[156:159], v[178:181], v[118:121]
	v_mfma_f32_16x16x32_bf16 v[114:117], v[164:167], v[178:181], v[114:117]
	v_mfma_f32_16x16x32_bf16 v[102:105], v[156:159], v[186:189], v[102:105]
	v_mfma_f32_16x16x32_bf16 v[98:101], v[164:167], v[186:189], v[98:101]
	v_mfma_f32_16x16x32_bf16 v[86:89], v[156:159], v[194:197], v[86:89]
	v_mfma_f32_16x16x32_bf16 v[82:85], v[164:167], v[194:197], v[82:85]
	v_mfma_f32_16x16x32_bf16 v[70:73], v[156:159], v[216:219], v[70:73]
	v_mfma_f32_16x16x32_bf16 v[66:69], v[164:167], v[216:219], v[66:69]
	v_mfma_f32_16x16x32_bf16 v[118:121], v[160:163], v[182:185], v[118:121]
	v_mfma_f32_16x16x32_bf16 v[114:117], v[168:171], v[182:185], v[114:117]
	v_mfma_f32_16x16x32_bf16 v[102:105], v[160:163], v[190:193], v[102:105]
	v_mfma_f32_16x16x32_bf16 v[98:101], v[168:171], v[190:193], v[98:101]
	v_mfma_f32_16x16x32_bf16 v[86:89], v[160:163], v[198:201], v[86:89]
	v_mfma_f32_16x16x32_bf16 v[82:85], v[168:171], v[198:201], v[82:85]
	v_mfma_f32_16x16x32_bf16 v[70:73], v[160:163], v[220:223], v[70:73]
	v_mfma_f32_16x16x32_bf16 v[66:69], v[168:171], v[220:223], v[66:69]
	s_setprio 0
	s_barrier
	s_add_i32 s20, s21, s9
	v_lshl_add_u64 v[202:203], s[56:57], 0, v[132:133]
	s_mov_b32 m0, s20
	ds_read_b128 v[178:181], v176 offset:16384
	ds_read_b128 v[182:185], v176 offset:17408
	ds_read_b128 v[186:189], v176 offset:18432
	ds_read_b128 v[190:193], v176 offset:19456
	ds_read_b128 v[194:197], v176 offset:20480
	ds_read_b128 v[198:201], v176 offset:21504
	ds_read_b128 v[216:219], v176 offset:22528
	ds_read_b128 v[220:223], v176 offset:23552
	global_load_lds_dwordx4 v[202:203], off
	s_add_i32 m0, s20, 0x2000
	s_add_u32 s20, s56, 0x40000
	v_lshl_add_u64 v[224:225], s[56:57], 0, v[130:131]
	s_addc_u32 s21, s57, 0
	s_add_i32 s6, s6, s9
	global_load_lds_dwordx4 v[224:225], off
	v_lshl_add_u64 v[226:227], s[20:21], 0, v[132:133]
	s_mov_b32 m0, s6
	v_lshl_add_u64 v[228:229], s[58:59], 0, v[130:131]
	global_load_lds_dwordx4 v[226:227], off
	v_lshl_add_u64 v[226:227], s[20:21], 0, v[130:131]
	s_add_i32 m0, s6, 0x2000
	s_nop 0
	global_load_lds_dwordx4 v[226:227], off
	v_lshl_add_u64 v[226:227], s[58:59], 0, v[132:133]
	s_mov_b32 m0, s60
	s_nop 0
	global_load_lds_dwordx4 v[226:227], off
	s_mov_b32 m0, s61
	s_nop 0
	global_load_lds_dwordx4 v[228:229], off
	s_waitcnt vmcnt(8)
	s_waitcnt lgkmcnt(0)
	s_barrier
	s_setprio 1
	v_mfma_f32_16x16x32_bf16 v[62:65], v[138:141], v[178:181], v[62:65]
	v_mfma_f32_16x16x32_bf16 v[58:61], v[146:149], v[178:181], v[58:61]
	v_mfma_f32_16x16x32_bf16 v[44:47], v[138:141], v[186:189], v[44:47]
	v_mfma_f32_16x16x32_bf16 v[40:43], v[146:149], v[186:189], v[40:43]
	v_mfma_f32_16x16x32_bf16 v[28:31], v[138:141], v[194:197], v[28:31]
	v_mfma_f32_16x16x32_bf16 v[24:27], v[146:149], v[194:197], v[24:27]
	v_mfma_f32_16x16x32_bf16 v[12:15], v[138:141], v[216:219], v[12:15]
	v_mfma_f32_16x16x32_bf16 v[8:11], v[146:149], v[216:219], v[8:11]
	v_mfma_f32_16x16x32_bf16 v[62:65], v[142:145], v[182:185], v[62:65]
	v_mfma_f32_16x16x32_bf16 v[58:61], v[150:153], v[182:185], v[58:61]
	v_mfma_f32_16x16x32_bf16 v[44:47], v[142:145], v[190:193], v[44:47]
	v_mfma_f32_16x16x32_bf16 v[40:43], v[150:153], v[190:193], v[40:43]
	v_mfma_f32_16x16x32_bf16 v[28:31], v[142:145], v[198:201], v[28:31]
	v_mfma_f32_16x16x32_bf16 v[24:27], v[150:153], v[198:201], v[24:27]
	v_mfma_f32_16x16x32_bf16 v[12:15], v[142:145], v[220:223], v[12:15]
	v_mfma_f32_16x16x32_bf16 v[8:11], v[150:153], v[220:223], v[8:11]
	v_mfma_f32_16x16x32_bf16 v[54:57], v[156:159], v[178:181], v[54:57]
	v_mfma_f32_16x16x32_bf16 v[50:53], v[164:167], v[178:181], v[50:53]
	v_mfma_f32_16x16x32_bf16 v[36:39], v[156:159], v[186:189], v[36:39]
	v_mfma_f32_16x16x32_bf16 v[32:35], v[164:167], v[186:189], v[32:35]
	v_mfma_f32_16x16x32_bf16 v[20:23], v[156:159], v[194:197], v[20:23]
	v_mfma_f32_16x16x32_bf16 v[16:19], v[164:167], v[194:197], v[16:19]
	v_mfma_f32_16x16x32_bf16 v[4:7], v[156:159], v[216:219], v[4:7]
	v_mfma_f32_16x16x32_bf16 v[0:3], v[164:167], v[216:219], v[0:3]
	v_mfma_f32_16x16x32_bf16 v[54:57], v[160:163], v[182:185], v[54:57]
	v_mfma_f32_16x16x32_bf16 v[50:53], v[168:171], v[182:185], v[50:53]
	v_mfma_f32_16x16x32_bf16 v[36:39], v[160:163], v[190:193], v[36:39]
	v_mfma_f32_16x16x32_bf16 v[32:35], v[168:171], v[190:193], v[32:35]
	v_mfma_f32_16x16x32_bf16 v[20:23], v[160:163], v[198:201], v[20:23]
	v_mfma_f32_16x16x32_bf16 v[16:19], v[168:171], v[198:201], v[16:19]
	v_mfma_f32_16x16x32_bf16 v[4:7], v[160:163], v[220:223], v[4:7]
	v_mfma_f32_16x16x32_bf16 v[0:3], v[168:171], v[220:223], v[0:3]
	s_setprio 0
	s_barrier
	s_add_i32 s6, 0, 0x18000
	v_add_u32_e32 v48, s6, v173
	s_add_i32 s26, 0, 0x1c000
	ds_read_b128 v[138:141], v48
	ds_read_b128 v[142:145], v48 offset:1024
	ds_read_b128 v[146:149], v48 offset:2048
	ds_read_b128 v[150:153], v48 offset:3072
	v_add_u32_e32 v48, s26, v173
	ds_read_b128 v[156:159], v48
	ds_read_b128 v[160:163], v48 offset:1024
	ds_read_b128 v[164:167], v48 offset:2048
	ds_read_b128 v[168:171], v48 offset:3072
	s_add_u32 s20, s58, 0x40000
	s_addc_u32 s21, s59, 0
	s_mov_b32 m0, s62
	v_lshl_add_u64 v[230:231], s[20:21], 0, v[132:133]
	ds_read_b128 v[178:181], v176 offset:32768
	ds_read_b128 v[182:185], v176 offset:33792
	ds_read_b128 v[186:189], v176 offset:34816
	ds_read_b128 v[190:193], v176 offset:35840
	ds_read_b128 v[194:197], v176 offset:36864
	ds_read_b128 v[198:201], v176 offset:37888
	ds_read_b128 v[216:219], v176 offset:38912
	ds_read_b128 v[220:223], v176 offset:39936
	global_load_lds_dwordx4 v[230:231], off
	v_lshl_add_u64 v[230:231], s[20:21], 0, v[130:131]
	s_mov_b32 m0, s63
	s_nop 0
	global_load_lds_dwordx4 v[230:231], off
	s_waitcnt vmcnt(8)
	s_waitcnt lgkmcnt(0)
	s_barrier
	s_setprio 1
	v_mfma_f32_16x16x32_bf16 v[126:129], v[138:141], v[178:181], v[126:129]
	v_mfma_f32_16x16x32_bf16 v[122:125], v[146:149], v[178:181], v[122:125]
	v_mfma_f32_16x16x32_bf16 v[110:113], v[138:141], v[186:189], v[110:113]
	v_mfma_f32_16x16x32_bf16 v[106:109], v[146:149], v[186:189], v[106:109]
	v_mfma_f32_16x16x32_bf16 v[94:97], v[138:141], v[194:197], v[94:97]
	v_mfma_f32_16x16x32_bf16 v[90:93], v[146:149], v[194:197], v[90:93]
	v_mfma_f32_16x16x32_bf16 v[78:81], v[138:141], v[216:219], v[78:81]
	v_mfma_f32_16x16x32_bf16 v[74:77], v[146:149], v[216:219], v[74:77]
	v_mfma_f32_16x16x32_bf16 v[126:129], v[142:145], v[182:185], v[126:129]
	v_mfma_f32_16x16x32_bf16 v[122:125], v[150:153], v[182:185], v[122:125]
	v_mfma_f32_16x16x32_bf16 v[110:113], v[142:145], v[190:193], v[110:113]
	v_mfma_f32_16x16x32_bf16 v[106:109], v[150:153], v[190:193], v[106:109]
	v_mfma_f32_16x16x32_bf16 v[94:97], v[142:145], v[198:201], v[94:97]
	v_mfma_f32_16x16x32_bf16 v[90:93], v[150:153], v[198:201], v[90:93]
	v_mfma_f32_16x16x32_bf16 v[78:81], v[142:145], v[220:223], v[78:81]
	v_mfma_f32_16x16x32_bf16 v[74:77], v[150:153], v[220:223], v[74:77]
	v_mfma_f32_16x16x32_bf16 v[118:121], v[156:159], v[178:181], v[118:121]
	v_mfma_f32_16x16x32_bf16 v[114:117], v[164:167], v[178:181], v[114:117]
	v_mfma_f32_16x16x32_bf16 v[102:105], v[156:159], v[186:189], v[102:105]
	v_mfma_f32_16x16x32_bf16 v[98:101], v[164:167], v[186:189], v[98:101]
	v_mfma_f32_16x16x32_bf16 v[86:89], v[156:159], v[194:197], v[86:89]
	v_mfma_f32_16x16x32_bf16 v[82:85], v[164:167], v[194:197], v[82:85]
	v_mfma_f32_16x16x32_bf16 v[70:73], v[156:159], v[216:219], v[70:73]
	v_mfma_f32_16x16x32_bf16 v[66:69], v[164:167], v[216:219], v[66:69]
	v_mfma_f32_16x16x32_bf16 v[118:121], v[160:163], v[182:185], v[118:121]
	v_mfma_f32_16x16x32_bf16 v[114:117], v[168:171], v[182:185], v[114:117]
	v_mfma_f32_16x16x32_bf16 v[102:105], v[160:163], v[190:193], v[102:105]
	v_mfma_f32_16x16x32_bf16 v[98:101], v[168:171], v[190:193], v[98:101]
	v_mfma_f32_16x16x32_bf16 v[86:89], v[160:163], v[198:201], v[86:89]
	v_mfma_f32_16x16x32_bf16 v[82:85], v[168:171], v[198:201], v[82:85]
	v_mfma_f32_16x16x32_bf16 v[70:73], v[160:163], v[220:223], v[70:73]
	v_mfma_f32_16x16x32_bf16 v[66:69], v[168:171], v[220:223], v[66:69]
	s_setprio 0
	s_barrier
	s_add_i32 s6, s6, s9
	v_lshl_add_u64 v[202:203], v[202:203], 0, s[30:31]
	s_mov_b32 m0, s6
	ds_read_b128 v[178:181], v176 offset:49152
	ds_read_b128 v[182:185], v176 offset:50176
	ds_read_b128 v[186:189], v176 offset:51200
	ds_read_b128 v[190:193], v176 offset:52224
	ds_read_b128 v[194:197], v176 offset:53248
	ds_read_b128 v[198:201], v176 offset:54272
	ds_read_b128 v[216:219], v176 offset:55296
	ds_read_b128 v[220:223], v176 offset:56320
	global_load_lds_dwordx4 v[202:203], off
	s_add_i32 m0, s6, 0x2000
	s_add_u32 s20, s56, 0x40080
	v_lshl_add_u64 v[202:203], v[224:225], 0, s[30:31]
	s_addc_u32 s21, s57, 0
	s_add_i32 s6, s26, s9
	global_load_lds_dwordx4 v[202:203], off
	v_lshl_add_u64 v[202:203], s[20:21], 0, v[132:133]
	s_mov_b32 m0, s6
	s_nop 0
	global_load_lds_dwordx4 v[202:203], off
	v_lshl_add_u64 v[202:203], s[20:21], 0, v[130:131]
	s_add_i32 m0, s6, 0x2000
	s_nop 0
	global_load_lds_dwordx4 v[202:203], off
	v_lshl_add_u64 v[202:203], v[226:227], 0, s[30:31]
	s_mov_b32 m0, s64
	s_nop 0
	global_load_lds_dwordx4 v[202:203], off
	v_lshl_add_u64 v[202:203], v[228:229], 0, s[30:31]
	s_mov_b32 m0, s65
	s_nop 0
	global_load_lds_dwordx4 v[202:203], off
	s_waitcnt vmcnt(8)
	s_waitcnt lgkmcnt(0)
	s_barrier
	s_setprio 1
	v_mfma_f32_16x16x32_bf16 v[62:65], v[138:141], v[178:181], v[62:65]
	v_mfma_f32_16x16x32_bf16 v[58:61], v[146:149], v[178:181], v[58:61]
	v_mfma_f32_16x16x32_bf16 v[44:47], v[138:141], v[186:189], v[44:47]
	v_mfma_f32_16x16x32_bf16 v[40:43], v[146:149], v[186:189], v[40:43]
	v_mfma_f32_16x16x32_bf16 v[28:31], v[138:141], v[194:197], v[28:31]
	v_mfma_f32_16x16x32_bf16 v[24:27], v[146:149], v[194:197], v[24:27]
	v_mfma_f32_16x16x32_bf16 v[12:15], v[138:141], v[216:219], v[12:15]
	v_mfma_f32_16x16x32_bf16 v[8:11], v[146:149], v[216:219], v[8:11]
	v_mfma_f32_16x16x32_bf16 v[62:65], v[142:145], v[182:185], v[62:65]
	v_mfma_f32_16x16x32_bf16 v[58:61], v[150:153], v[182:185], v[58:61]
	v_mfma_f32_16x16x32_bf16 v[44:47], v[142:145], v[190:193], v[44:47]
	v_mfma_f32_16x16x32_bf16 v[40:43], v[150:153], v[190:193], v[40:43]
	v_mfma_f32_16x16x32_bf16 v[28:31], v[142:145], v[198:201], v[28:31]
	v_mfma_f32_16x16x32_bf16 v[24:27], v[150:153], v[198:201], v[24:27]
	v_mfma_f32_16x16x32_bf16 v[12:15], v[142:145], v[220:223], v[12:15]
	v_mfma_f32_16x16x32_bf16 v[8:11], v[150:153], v[220:223], v[8:11]
	v_mfma_f32_16x16x32_bf16 v[54:57], v[156:159], v[178:181], v[54:57]
	v_mfma_f32_16x16x32_bf16 v[50:53], v[164:167], v[178:181], v[50:53]
	v_mfma_f32_16x16x32_bf16 v[36:39], v[156:159], v[186:189], v[36:39]
	v_mfma_f32_16x16x32_bf16 v[32:35], v[164:167], v[186:189], v[32:35]
	v_mfma_f32_16x16x32_bf16 v[20:23], v[156:159], v[194:197], v[20:23]
	v_mfma_f32_16x16x32_bf16 v[16:19], v[164:167], v[194:197], v[16:19]
	v_mfma_f32_16x16x32_bf16 v[4:7], v[156:159], v[216:219], v[4:7]
	v_mfma_f32_16x16x32_bf16 v[0:3], v[164:167], v[216:219], v[0:3]
	v_mfma_f32_16x16x32_bf16 v[54:57], v[160:163], v[182:185], v[54:57]
	v_mfma_f32_16x16x32_bf16 v[50:53], v[168:171], v[182:185], v[50:53]
	v_mfma_f32_16x16x32_bf16 v[36:39], v[160:163], v[190:193], v[36:39]
	v_mfma_f32_16x16x32_bf16 v[32:35], v[168:171], v[190:193], v[32:35]
	v_mfma_f32_16x16x32_bf16 v[20:23], v[160:163], v[198:201], v[20:23]
	v_mfma_f32_16x16x32_bf16 v[16:19], v[168:171], v[198:201], v[16:19]
	v_mfma_f32_16x16x32_bf16 v[4:7], v[160:163], v[220:223], v[4:7]
	v_mfma_f32_16x16x32_bf16 v[0:3], v[168:171], v[220:223], v[0:3]
	s_setprio 0
	s_add_i32 s68, s68, 2
	s_add_u32 s54, s54, 0x100
	s_addc_u32 s55, s55, 0
	s_add_u32 s66, s66, 0x100
	s_addc_u32 s67, s67, 0
	s_add_u32 s6, s54, 0xfffc0080
	s_addc_u32 s20, s55, -1
	s_cmp_eq_u32 s68, 12
	s_cselect_b32 s59, s33, s20
	s_cselect_b32 s58, s39, s6
	s_cselect_b32 s57, s45, s67
	s_cselect_b32 s56, s47, s66
	s_cmp_gt_u32 s68, 13
	s_barrier
	s_cbranch_scc0 .LBB0_248
	s_and_b64 vcc, exec, s[42:43]
	s_cbranch_vccz .LBB0_251
	s_barrier

.LBB0_471:
	s_add_u32 s69, s52, 0x100
	v_mov_b32_e32 v0, 0
	s_addc_u32 s70, s53, 0
	s_mov_b32 s71, -2
	v_mov_b32_e32 v1, v0
	v_mov_b32_e32 v2, v0
	v_mov_b32_e32 v3, v0
	v_mov_b32_e32 v4, v0
	v_mov_b32_e32 v5, v0
	v_mov_b32_e32 v6, v0
	v_mov_b32_e32 v7, v0
	v_mov_b32_e32 v16, v0
	v_mov_b32_e32 v17, v0
	v_mov_b32_e32 v18, v0
	v_mov_b32_e32 v19, v0
	v_mov_b32_e32 v20, v0
	v_mov_b32_e32 v21, v0
	v_mov_b32_e32 v22, v0
	v_mov_b32_e32 v23, v0
	v_mov_b32_e32 v32, v0
	v_mov_b32_e32 v33, v0
	v_mov_b32_e32 v34, v0
	v_mov_b32_e32 v35, v0
	v_mov_b32_e32 v36, v0
	v_mov_b32_e32 v37, v0
	v_mov_b32_e32 v38, v0
	v_mov_b32_e32 v39, v0
	v_mov_b32_e32 v50, v0
	v_mov_b32_e32 v51, v0
	v_mov_b32_e32 v52, v0
	v_mov_b32_e32 v53, v0
	v_mov_b32_e32 v54, v0
	v_mov_b32_e32 v55, v0
	v_mov_b32_e32 v56, v0
	v_mov_b32_e32 v57, v0
	v_mov_b32_e32 v8, v0
	v_mov_b32_e32 v9, v0
	v_mov_b32_e32 v10, v0
	v_mov_b32_e32 v11, v0
	v_mov_b32_e32 v12, v0
	v_mov_b32_e32 v13, v0
	v_mov_b32_e32 v14, v0
	v_mov_b32_e32 v15, v0
	v_mov_b32_e32 v24, v0
	v_mov_b32_e32 v25, v0
	v_mov_b32_e32 v26, v0
	v_mov_b32_e32 v27, v0
	v_mov_b32_e32 v28, v0
	v_mov_b32_e32 v29, v0
	v_mov_b32_e32 v30, v0
	v_mov_b32_e32 v31, v0
	v_mov_b32_e32 v40, v0
	v_mov_b32_e32 v41, v0
	v_mov_b32_e32 v42, v0
	v_mov_b32_e32 v43, v0
	v_mov_b32_e32 v44, v0
	v_mov_b32_e32 v45, v0
	v_mov_b32_e32 v46, v0
	v_mov_b32_e32 v47, v0
	v_mov_b32_e32 v58, v0
	v_mov_b32_e32 v59, v0
	v_mov_b32_e32 v60, v0
	v_mov_b32_e32 v61, v0
	v_mov_b32_e32 v62, v0
	v_mov_b32_e32 v63, v0
	v_mov_b32_e32 v64, v0
	v_mov_b32_e32 v65, v0
	v_mov_b32_e32 v66, v0
	v_mov_b32_e32 v67, v0
	v_mov_b32_e32 v68, v0
	v_mov_b32_e32 v69, v0
	v_mov_b32_e32 v70, v0
	v_mov_b32_e32 v71, v0
	v_mov_b32_e32 v72, v0
	v_mov_b32_e32 v73, v0
	v_mov_b32_e32 v82, v0
	v_mov_b32_e32 v83, v0
	v_mov_b32_e32 v84, v0
	v_mov_b32_e32 v85, v0
	v_mov_b32_e32 v86, v0
	v_mov_b32_e32 v87, v0
	v_mov_b32_e32 v88, v0
	v_mov_b32_e32 v89, v0
	v_mov_b32_e32 v98, v0
	v_mov_b32_e32 v99, v0
	v_mov_b32_e32 v100, v0
	v_mov_b32_e32 v101, v0
	v_mov_b32_e32 v102, v0
	v_mov_b32_e32 v103, v0
	v_mov_b32_e32 v104, v0
	v_mov_b32_e32 v105, v0
	v_mov_b32_e32 v114, v0
	v_mov_b32_e32 v115, v0
	v_mov_b32_e32 v116, v0
	v_mov_b32_e32 v117, v0
	v_mov_b32_e32 v118, v0
	v_mov_b32_e32 v119, v0
	v_mov_b32_e32 v120, v0
	v_mov_b32_e32 v121, v0
	v_mov_b32_e32 v74, v0
	v_mov_b32_e32 v75, v0
	v_mov_b32_e32 v76, v0
	v_mov_b32_e32 v77, v0
	v_mov_b32_e32 v78, v0
	v_mov_b32_e32 v79, v0
	v_mov_b32_e32 v80, v0
	v_mov_b32_e32 v81, v0
	v_mov_b32_e32 v90, v0
	v_mov_b32_e32 v91, v0
	v_mov_b32_e32 v92, v0
	v_mov_b32_e32 v93, v0
	v_mov_b32_e32 v94, v0
	v_mov_b32_e32 v95, v0
	v_mov_b32_e32 v96, v0
	v_mov_b32_e32 v97, v0
	v_mov_b32_e32 v106, v0
	v_mov_b32_e32 v107, v0
	v_mov_b32_e32 v108, v0
	v_mov_b32_e32 v109, v0
	v_mov_b32_e32 v110, v0
	v_mov_b32_e32 v111, v0
	v_mov_b32_e32 v112, v0
	v_mov_b32_e32 v113, v0
	v_mov_b32_e32 v126, v0
	v_mov_b32_e32 v127, v0
	v_mov_b32_e32 v128, v0
	v_mov_b32_e32 v129, v0
	v_mov_b32_e32 v134, v0
	v_mov_b32_e32 v135, v0
	v_mov_b32_e32 v136, v0
	v_mov_b32_e32 v137, v0
	s_add_u32 s52, s50, 0x100
	s_addc_u32 s53, s51, 0
	s_cmp_eq_u32 s71, 40
	s_cselect_b32 s57, s47, s53
	s_cselect_b32 s56, s46, s52
	s_cselect_b32 s55, s49, s70
	s_cselect_b32 s54, s48, s69
.LBB0_472:
	s_add_i32 s6, 0, 0x10000
	v_add_u32_e32 v48, s6, v183
	s_add_i32 s26, 0, 0x14000
	ds_read_b128 v[122:125], v48
	ds_read_b128 v[130:133], v48 offset:1024
	ds_read_b128 v[138:141], v48 offset:2048
	ds_read_b128 v[142:145], v48 offset:3072
	v_add_u32_e32 v48, s26, v183
	ds_read_b128 v[146:149], v48
	ds_read_b128 v[150:153], v48 offset:1024
	ds_read_b128 v[168:171], v48 offset:2048
	ds_read_b128 v[172:175], v48 offset:3072
	v_lshl_add_u64 v[180:181], s[50:51], 0, v[164:165]
	s_add_i32 m0, s59, 0xc000
	ds_read_b128 v[176:179], v185
	ds_read_b128 v[186:189], v185 offset:1024
	ds_read_b128 v[190:193], v185 offset:2048
	ds_read_b128 v[194:197], v185 offset:3072
	ds_read_b128 v[198:201], v185 offset:4096
	ds_read_b128 v[216:219], v185 offset:5120
	ds_read_b128 v[220:223], v185 offset:6144
	ds_read_b128 v[224:227], v185 offset:7168
	global_load_lds_dwordx4 v[180:181], off
	v_lshl_add_u64 v[180:181], s[50:51], 0, v[166:167]
	s_add_i32 m0, s59, 0xe000
	s_nop 0
	global_load_lds_dwordx4 v[180:181], off
	s_waitcnt vmcnt(8)
	s_waitcnt lgkmcnt(0)
	s_barrier
	s_setprio 1
	v_mfma_f32_16x16x32_bf16 v[134:137], v[122:125], v[176:179], v[134:137]
	v_mfma_f32_16x16x32_bf16 v[126:129], v[138:141], v[176:179], v[126:129]
	v_mfma_f32_16x16x32_bf16 v[110:113], v[122:125], v[190:193], v[110:113]
	v_mfma_f32_16x16x32_bf16 v[106:109], v[138:141], v[190:193], v[106:109]
	v_mfma_f32_16x16x32_bf16 v[94:97], v[122:125], v[198:201], v[94:97]
	v_mfma_f32_16x16x32_bf16 v[90:93], v[138:141], v[198:201], v[90:93]
	v_mfma_f32_16x16x32_bf16 v[78:81], v[122:125], v[220:223], v[78:81]
	v_mfma_f32_16x16x32_bf16 v[74:77], v[138:141], v[220:223], v[74:77]
	v_mfma_f32_16x16x32_bf16 v[134:137], v[130:133], v[186:189], v[134:137]
	v_mfma_f32_16x16x32_bf16 v[126:129], v[142:145], v[186:189], v[126:129]
	v_mfma_f32_16x16x32_bf16 v[110:113], v[130:133], v[194:197], v[110:113]
	v_mfma_f32_16x16x32_bf16 v[106:109], v[142:145], v[194:197], v[106:109]
	v_mfma_f32_16x16x32_bf16 v[94:97], v[130:133], v[216:219], v[94:97]
	v_mfma_f32_16x16x32_bf16 v[90:93], v[142:145], v[216:219], v[90:93]
	v_mfma_f32_16x16x32_bf16 v[78:81], v[130:133], v[224:227], v[78:81]
	v_mfma_f32_16x16x32_bf16 v[74:77], v[142:145], v[224:227], v[74:77]
	v_mfma_f32_16x16x32_bf16 v[118:121], v[146:149], v[176:179], v[118:121]
	v_mfma_f32_16x16x32_bf16 v[114:117], v[168:171], v[176:179], v[114:117]
	v_mfma_f32_16x16x32_bf16 v[102:105], v[146:149], v[190:193], v[102:105]
	v_mfma_f32_16x16x32_bf16 v[98:101], v[168:171], v[190:193], v[98:101]
	v_mfma_f32_16x16x32_bf16 v[86:89], v[146:149], v[198:201], v[86:89]
	v_mfma_f32_16x16x32_bf16 v[82:85], v[168:171], v[198:201], v[82:85]
	v_mfma_f32_16x16x32_bf16 v[70:73], v[146:149], v[220:223], v[70:73]
	v_mfma_f32_16x16x32_bf16 v[66:69], v[168:171], v[220:223], v[66:69]
	v_mfma_f32_16x16x32_bf16 v[118:121], v[150:153], v[186:189], v[118:121]
	v_mfma_f32_16x16x32_bf16 v[114:117], v[172:175], v[186:189], v[114:117]
	v_mfma_f32_16x16x32_bf16 v[102:105], v[150:153], v[194:197], v[102:105]
	v_mfma_f32_16x16x32_bf16 v[98:101], v[172:175], v[194:197], v[98:101]
	v_mfma_f32_16x16x32_bf16 v[86:89], v[150:153], v[216:219], v[86:89]
	v_mfma_f32_16x16x32_bf16 v[82:85], v[172:175], v[216:219], v[82:85]
	v_mfma_f32_16x16x32_bf16 v[70:73], v[150:153], v[224:227], v[70:73]
	v_mfma_f32_16x16x32_bf16 v[66:69], v[172:175], v[224:227], v[66:69]
	s_setprio 0
	s_barrier
	s_add_i32 s6, s6, s58
	v_lshl_add_u64 v[180:181], s[54:55], 0, v[158:159]
	s_mov_b32 m0, s6
	ds_read_b128 v[176:179], v185 offset:16384
	ds_read_b128 v[186:189], v185 offset:17408
	ds_read_b128 v[190:193], v185 offset:18432
	ds_read_b128 v[194:197], v185 offset:19456
	ds_read_b128 v[198:201], v185 offset:20480
	ds_read_b128 v[216:219], v185 offset:21504
	ds_read_b128 v[220:223], v185 offset:22528
	ds_read_b128 v[224:227], v185 offset:23552
	global_load_lds_dwordx4 v[180:181], off
	s_add_i32 m0, s6, 0x2000
	s_add_u32 s20, s54, 0xb0000
	v_lshl_add_u64 v[202:203], s[54:55], 0, v[162:163]
	s_addc_u32 s21, s55, 0
	s_add_i32 s6, s26, s58
	global_load_lds_dwordx4 v[202:203], off
	v_lshl_add_u64 v[228:229], s[20:21], 0, v[158:159]
	s_mov_b32 m0, s6
	v_lshl_add_u64 v[230:231], s[56:57], 0, v[160:161]
	global_load_lds_dwordx4 v[228:229], off
	v_lshl_add_u64 v[228:229], s[20:21], 0, v[162:163]
	s_add_i32 m0, s6, 0x2000
	s_nop 0
	global_load_lds_dwordx4 v[228:229], off
	v_lshl_add_u64 v[228:229], s[56:57], 0, v[156:157]
	s_mov_b32 m0, s59
	s_nop 0
	global_load_lds_dwordx4 v[228:229], off
	s_mov_b32 m0, s60
	s_nop 0
	global_load_lds_dwordx4 v[230:231], off
	s_waitcnt vmcnt(8)
	s_waitcnt lgkmcnt(0)
	s_barrier
	s_setprio 1
	v_mfma_f32_16x16x32_bf16 v[62:65], v[122:125], v[176:179], v[62:65]
	v_mfma_f32_16x16x32_bf16 v[58:61], v[138:141], v[176:179], v[58:61]
	v_mfma_f32_16x16x32_bf16 v[44:47], v[122:125], v[190:193], v[44:47]
	v_mfma_f32_16x16x32_bf16 v[40:43], v[138:141], v[190:193], v[40:43]
	v_mfma_f32_16x16x32_bf16 v[28:31], v[122:125], v[198:201], v[28:31]
	v_mfma_f32_16x16x32_bf16 v[24:27], v[138:141], v[198:201], v[24:27]
	v_mfma_f32_16x16x32_bf16 v[12:15], v[122:125], v[220:223], v[12:15]
	v_mfma_f32_16x16x32_bf16 v[8:11], v[138:141], v[220:223], v[8:11]
	v_mfma_f32_16x16x32_bf16 v[62:65], v[130:133], v[186:189], v[62:65]
	v_mfma_f32_16x16x32_bf16 v[58:61], v[142:145], v[186:189], v[58:61]
	v_mfma_f32_16x16x32_bf16 v[44:47], v[130:133], v[194:197], v[44:47]
	v_mfma_f32_16x16x32_bf16 v[40:43], v[142:145], v[194:197], v[40:43]
	v_mfma_f32_16x16x32_bf16 v[28:31], v[130:133], v[216:219], v[28:31]
	v_mfma_f32_16x16x32_bf16 v[24:27], v[142:145], v[216:219], v[24:27]
	v_mfma_f32_16x16x32_bf16 v[12:15], v[130:133], v[224:227], v[12:15]
	v_mfma_f32_16x16x32_bf16 v[8:11], v[142:145], v[224:227], v[8:11]
	v_mfma_f32_16x16x32_bf16 v[54:57], v[146:149], v[176:179], v[54:57]
	v_mfma_f32_16x16x32_bf16 v[50:53], v[168:171], v[176:179], v[50:53]
	v_mfma_f32_16x16x32_bf16 v[36:39], v[146:149], v[190:193], v[36:39]
	v_mfma_f32_16x16x32_bf16 v[32:35], v[168:171], v[190:193], v[32:35]
	v_mfma_f32_16x16x32_bf16 v[20:23], v[146:149], v[198:201], v[20:23]
	v_mfma_f32_16x16x32_bf16 v[16:19], v[168:171], v[198:201], v[16:19]
	v_mfma_f32_16x16x32_bf16 v[4:7], v[146:149], v[220:223], v[4:7]
	v_mfma_f32_16x16x32_bf16 v[0:3], v[168:171], v[220:223], v[0:3]
	v_mfma_f32_16x16x32_bf16 v[54:57], v[150:153], v[186:189], v[54:57]
	v_mfma_f32_16x16x32_bf16 v[50:53], v[172:175], v[186:189], v[50:53]
	v_mfma_f32_16x16x32_bf16 v[36:39], v[150:153], v[194:197], v[36:39]
	v_mfma_f32_16x16x32_bf16 v[32:35], v[172:175], v[194:197], v[32:35]
	v_mfma_f32_16x16x32_bf16 v[20:23], v[150:153], v[216:219], v[20:23]
	v_mfma_f32_16x16x32_bf16 v[16:19], v[172:175], v[216:219], v[16:19]
	v_mfma_f32_16x16x32_bf16 v[4:7], v[150:153], v[224:227], v[4:7]
	v_mfma_f32_16x16x32_bf16 v[0:3], v[172:175], v[224:227], v[0:3]
	s_setprio 0
	s_barrier
	s_add_i32 s6, 0, 0x18000
	v_add_u32_e32 v48, s6, v183
	s_add_i32 s26, 0, 0x1c000
	ds_read_b128 v[122:125], v48
	ds_read_b128 v[130:133], v48 offset:1024
	ds_read_b128 v[138:141], v48 offset:2048
	ds_read_b128 v[142:145], v48 offset:3072
	v_add_u32_e32 v48, s26, v183
	ds_read_b128 v[146:149], v48
	ds_read_b128 v[150:153], v48 offset:1024
	ds_read_b128 v[168:171], v48 offset:2048
	ds_read_b128 v[172:175], v48 offset:3072
	s_add_u32 s20, s56, 0xb0000
	s_addc_u32 s21, s57, 0
	s_mov_b32 m0, s61
	v_lshl_add_u64 v[232:233], s[20:21], 0, v[156:157]
	ds_read_b128 v[176:179], v185 offset:32768
	ds_read_b128 v[186:189], v185 offset:33792
	ds_read_b128 v[190:193], v185 offset:34816
	ds_read_b128 v[194:197], v185 offset:35840
	ds_read_b128 v[198:201], v185 offset:36864
	ds_read_b128 v[216:219], v185 offset:37888
	ds_read_b128 v[220:223], v185 offset:38912
	ds_read_b128 v[224:227], v185 offset:39936
	global_load_lds_dwordx4 v[232:233], off
	v_lshl_add_u64 v[232:233], s[20:21], 0, v[160:161]
	s_mov_b32 m0, s62
	s_nop 0
	global_load_lds_dwordx4 v[232:233], off
	s_waitcnt vmcnt(8)
	s_waitcnt lgkmcnt(0)
	s_barrier
	s_setprio 1
	v_mfma_f32_16x16x32_bf16 v[134:137], v[122:125], v[176:179], v[134:137]
	v_mfma_f32_16x16x32_bf16 v[126:129], v[138:141], v[176:179], v[126:129]
	v_mfma_f32_16x16x32_bf16 v[110:113], v[122:125], v[190:193], v[110:113]
	v_mfma_f32_16x16x32_bf16 v[106:109], v[138:141], v[190:193], v[106:109]
	v_mfma_f32_16x16x32_bf16 v[94:97], v[122:125], v[198:201], v[94:97]
	v_mfma_f32_16x16x32_bf16 v[90:93], v[138:141], v[198:201], v[90:93]
	v_mfma_f32_16x16x32_bf16 v[78:81], v[122:125], v[220:223], v[78:81]
	v_mfma_f32_16x16x32_bf16 v[74:77], v[138:141], v[220:223], v[74:77]
	v_mfma_f32_16x16x32_bf16 v[134:137], v[130:133], v[186:189], v[134:137]
	v_mfma_f32_16x16x32_bf16 v[126:129], v[142:145], v[186:189], v[126:129]
	v_mfma_f32_16x16x32_bf16 v[110:113], v[130:133], v[194:197], v[110:113]
	v_mfma_f32_16x16x32_bf16 v[106:109], v[142:145], v[194:197], v[106:109]
	v_mfma_f32_16x16x32_bf16 v[94:97], v[130:133], v[216:219], v[94:97]
	v_mfma_f32_16x16x32_bf16 v[90:93], v[142:145], v[216:219], v[90:93]
	v_mfma_f32_16x16x32_bf16 v[78:81], v[130:133], v[224:227], v[78:81]
	v_mfma_f32_16x16x32_bf16 v[74:77], v[142:145], v[224:227], v[74:77]
	v_mfma_f32_16x16x32_bf16 v[118:121], v[146:149], v[176:179], v[118:121]
	v_mfma_f32_16x16x32_bf16 v[114:117], v[168:171], v[176:179], v[114:117]
	v_mfma_f32_16x16x32_bf16 v[102:105], v[146:149], v[190:193], v[102:105]
	v_mfma_f32_16x16x32_bf16 v[98:101], v[168:171], v[190:193], v[98:101]
	v_mfma_f32_16x16x32_bf16 v[86:89], v[146:149], v[198:201], v[86:89]
	v_mfma_f32_16x16x32_bf16 v[82:85], v[168:171], v[198:201], v[82:85]
	v_mfma_f32_16x16x32_bf16 v[70:73], v[146:149], v[220:223], v[70:73]
	v_mfma_f32_16x16x32_bf16 v[66:69], v[168:171], v[220:223], v[66:69]
	v_mfma_f32_16x16x32_bf16 v[118:121], v[150:153], v[186:189], v[118:121]
	v_mfma_f32_16x16x32_bf16 v[114:117], v[172:175], v[186:189], v[114:117]
	v_mfma_f32_16x16x32_bf16 v[102:105], v[150:153], v[194:197], v[102:105]
	v_mfma_f32_16x16x32_bf16 v[98:101], v[172:175], v[194:197], v[98:101]
	v_mfma_f32_16x16x32_bf16 v[86:89], v[150:153], v[216:219], v[86:89]
	v_mfma_f32_16x16x32_bf16 v[82:85], v[172:175], v[216:219], v[82:85]
	v_mfma_f32_16x16x32_bf16 v[70:73], v[150:153], v[224:227], v[70:73]
	v_mfma_f32_16x16x32_bf16 v[66:69], v[172:175], v[224:227], v[66:69]
	s_setprio 0
	s_barrier
	s_add_i32 s6, s6, s58
	v_lshl_add_u64 v[180:181], v[180:181], 0, s[30:31]
	s_mov_b32 m0, s6
	ds_read_b128 v[176:179], v185 offset:49152
	ds_read_b128 v[186:189], v185 offset:50176
	ds_read_b128 v[190:193], v185 offset:51200
	ds_read_b128 v[194:197], v185 offset:52224
	ds_read_b128 v[198:201], v185 offset:53248
	ds_read_b128 v[216:219], v185 offset:54272
	ds_read_b128 v[220:223], v185 offset:55296
	ds_read_b128 v[224:227], v185 offset:56320
	global_load_lds_dwordx4 v[180:181], off
	s_add_i32 m0, s6, 0x2000
	s_add_u32 s20, s54, 0xb0080
	v_lshl_add_u64 v[180:181], v[202:203], 0, s[30:31]
	s_addc_u32 s21, s55, 0
	s_add_i32 s6, s26, s58
	global_load_lds_dwordx4 v[180:181], off
	v_lshl_add_u64 v[180:181], s[20:21], 0, v[158:159]
	s_mov_b32 m0, s6
	s_nop 0
	global_load_lds_dwordx4 v[180:181], off
	v_lshl_add_u64 v[180:181], s[20:21], 0, v[162:163]
	s_add_i32 m0, s6, 0x2000
	s_nop 0
	global_load_lds_dwordx4 v[180:181], off
	v_lshl_add_u64 v[180:181], v[228:229], 0, s[30:31]
	s_mov_b32 m0, s63
	s_nop 0
	global_load_lds_dwordx4 v[180:181], off
	v_lshl_add_u64 v[180:181], v[230:231], 0, s[30:31]
	s_mov_b32 m0, s64
	s_nop 0
	global_load_lds_dwordx4 v[180:181], off
	s_waitcnt vmcnt(8)
	s_waitcnt lgkmcnt(0)
	s_barrier
	s_setprio 1
	v_mfma_f32_16x16x32_bf16 v[62:65], v[122:125], v[176:179], v[62:65]
	v_mfma_f32_16x16x32_bf16 v[58:61], v[138:141], v[176:179], v[58:61]
	v_mfma_f32_16x16x32_bf16 v[44:47], v[122:125], v[190:193], v[44:47]
	v_mfma_f32_16x16x32_bf16 v[40:43], v[138:141], v[190:193], v[40:43]
	v_mfma_f32_16x16x32_bf16 v[28:31], v[122:125], v[198:201], v[28:31]
	v_mfma_f32_16x16x32_bf16 v[24:27], v[138:141], v[198:201], v[24:27]
	v_mfma_f32_16x16x32_bf16 v[12:15], v[122:125], v[220:223], v[12:15]
	v_mfma_f32_16x16x32_bf16 v[8:11], v[138:141], v[220:223], v[8:11]
	v_mfma_f32_16x16x32_bf16 v[62:65], v[130:133], v[186:189], v[62:65]
	v_mfma_f32_16x16x32_bf16 v[58:61], v[142:145], v[186:189], v[58:61]
	v_mfma_f32_16x16x32_bf16 v[44:47], v[130:133], v[194:197], v[44:47]
	v_mfma_f32_16x16x32_bf16 v[40:43], v[142:145], v[194:197], v[40:43]
	v_mfma_f32_16x16x32_bf16 v[28:31], v[130:133], v[216:219], v[28:31]
	v_mfma_f32_16x16x32_bf16 v[24:27], v[142:145], v[216:219], v[24:27]
	v_mfma_f32_16x16x32_bf16 v[12:15], v[130:133], v[224:227], v[12:15]
	v_mfma_f32_16x16x32_bf16 v[8:11], v[142:145], v[224:227], v[8:11]
	v_mfma_f32_16x16x32_bf16 v[54:57], v[146:149], v[176:179], v[54:57]
	v_mfma_f32_16x16x32_bf16 v[50:53], v[168:171], v[176:179], v[50:53]
	v_mfma_f32_16x16x32_bf16 v[36:39], v[146:149], v[190:193], v[36:39]
	v_mfma_f32_16x16x32_bf16 v[32:35], v[168:171], v[190:193], v[32:35]
	v_mfma_f32_16x16x32_bf16 v[20:23], v[146:149], v[198:201], v[20:23]
	v_mfma_f32_16x16x32_bf16 v[16:19], v[168:171], v[198:201], v[16:19]
	v_mfma_f32_16x16x32_bf16 v[4:7], v[146:149], v[220:223], v[4:7]
	v_mfma_f32_16x16x32_bf16 v[0:3], v[168:171], v[220:223], v[0:3]
	v_mfma_f32_16x16x32_bf16 v[54:57], v[150:153], v[186:189], v[54:57]
	v_mfma_f32_16x16x32_bf16 v[50:53], v[172:175], v[186:189], v[50:53]
	v_mfma_f32_16x16x32_bf16 v[36:39], v[150:153], v[194:197], v[36:39]
	v_mfma_f32_16x16x32_bf16 v[32:35], v[172:175], v[194:197], v[32:35]
	v_mfma_f32_16x16x32_bf16 v[20:23], v[150:153], v[216:219], v[20:23]
	v_mfma_f32_16x16x32_bf16 v[16:19], v[172:175], v[216:219], v[16:19]
	v_mfma_f32_16x16x32_bf16 v[4:7], v[150:153], v[224:227], v[4:7]
	v_mfma_f32_16x16x32_bf16 v[0:3], v[172:175], v[224:227], v[0:3]
	s_setprio 0
	s_add_i32 s71, s71, 2
	s_add_u32 s69, s69, 0x100
	s_addc_u32 s70, s70, 0
	s_mov_b64 s[50:51], s[52:53]
	s_add_u32 s52, s50, 0x100
	s_addc_u32 s53, s51, 0
	s_cmp_eq_u32 s71, 40
	s_cselect_b32 s57, s47, s53
	s_cselect_b32 s56, s46, s52
	s_cselect_b32 s55, s49, s70
	s_cselect_b32 s54, s48, s69
	s_cmp_gt_u32 s71, 41
	s_barrier
	s_cbranch_scc0 .LBB0_472
	s_and_b64 vcc, exec, s[44:45]
	s_cbranch_vccz .LBB0_475
	s_barrier

.LBB0_584:
	s_ashr_i32 s51, s50, 31
	s_lshl_b64 s[20:21], s[50:51], 19
	s_add_u32 s56, s16, s20
	s_addc_u32 s57, s17, s21
	s_and_b64 s[20:21], s[54:55], exec
	s_cselect_b32 s18, s57, s61
	s_cselect_b32 s33, s56, s60
	s_ashr_i32 s53, s52, 31
	s_lshl_b64 s[20:21], s[52:53], 19
	s_add_u32 s58, s8, s20
	s_addc_u32 s59, s9, s21
	s_and_b64 s[20:21], s[54:55], exec
	s_cselect_b32 s43, s59, s63
	s_cselect_b32 s45, s58, s62
	s_add_u32 s60, s60, 0x40080
	s_addc_u32 s61, s61, 0
	s_add_u32 s51, s62, 0x100
	v_mov_b32_e32 v0, 0
	s_addc_u32 s53, s63, 0
	s_mov_b32 s90, -2
	v_mov_b32_e32 v1, v0
	v_mov_b32_e32 v2, v0
	v_mov_b32_e32 v3, v0
	v_mov_b32_e32 v4, v0
	v_mov_b32_e32 v5, v0
	v_mov_b32_e32 v6, v0
	v_mov_b32_e32 v7, v0
	v_mov_b32_e32 v16, v0
	v_mov_b32_e32 v17, v0
	v_mov_b32_e32 v18, v0
	v_mov_b32_e32 v19, v0
	v_mov_b32_e32 v20, v0
	v_mov_b32_e32 v21, v0
	v_mov_b32_e32 v22, v0
	v_mov_b32_e32 v23, v0
	v_mov_b32_e32 v32, v0
	v_mov_b32_e32 v33, v0
	v_mov_b32_e32 v34, v0
	v_mov_b32_e32 v35, v0
	v_mov_b32_e32 v36, v0
	v_mov_b32_e32 v37, v0
	v_mov_b32_e32 v38, v0
	v_mov_b32_e32 v39, v0
	v_mov_b32_e32 v50, v0
	v_mov_b32_e32 v51, v0
	v_mov_b32_e32 v52, v0
	v_mov_b32_e32 v53, v0
	v_mov_b32_e32 v54, v0
	v_mov_b32_e32 v55, v0
	v_mov_b32_e32 v56, v0
	v_mov_b32_e32 v57, v0
	v_mov_b32_e32 v8, v0
	v_mov_b32_e32 v9, v0
	v_mov_b32_e32 v10, v0
	v_mov_b32_e32 v11, v0
	v_mov_b32_e32 v12, v0
	v_mov_b32_e32 v13, v0
	v_mov_b32_e32 v14, v0
	v_mov_b32_e32 v15, v0
	v_mov_b32_e32 v24, v0
	v_mov_b32_e32 v25, v0
	v_mov_b32_e32 v26, v0
	v_mov_b32_e32 v27, v0
	v_mov_b32_e32 v28, v0
	v_mov_b32_e32 v29, v0
	v_mov_b32_e32 v30, v0
	v_mov_b32_e32 v31, v0
	v_mov_b32_e32 v40, v0
	v_mov_b32_e32 v41, v0
	v_mov_b32_e32 v42, v0
	v_mov_b32_e32 v43, v0
	v_mov_b32_e32 v44, v0
	v_mov_b32_e32 v45, v0
	v_mov_b32_e32 v46, v0
	v_mov_b32_e32 v47, v0
	v_mov_b32_e32 v58, v0
	v_mov_b32_e32 v59, v0
	v_mov_b32_e32 v60, v0
	v_mov_b32_e32 v61, v0
	v_mov_b32_e32 v62, v0
	v_mov_b32_e32 v63, v0
	v_mov_b32_e32 v64, v0
	v_mov_b32_e32 v65, v0
	v_mov_b32_e32 v66, v0
	v_mov_b32_e32 v67, v0
	v_mov_b32_e32 v68, v0
	v_mov_b32_e32 v69, v0
	v_mov_b32_e32 v70, v0
	v_mov_b32_e32 v71, v0
	v_mov_b32_e32 v72, v0
	v_mov_b32_e32 v73, v0
	v_mov_b32_e32 v82, v0
	v_mov_b32_e32 v83, v0
	v_mov_b32_e32 v84, v0
	v_mov_b32_e32 v85, v0
	v_mov_b32_e32 v86, v0
	v_mov_b32_e32 v87, v0
	v_mov_b32_e32 v88, v0
	v_mov_b32_e32 v89, v0
	v_mov_b32_e32 v98, v0
	v_mov_b32_e32 v99, v0
	v_mov_b32_e32 v100, v0
	v_mov_b32_e32 v101, v0
	v_mov_b32_e32 v102, v0
	v_mov_b32_e32 v103, v0
	v_mov_b32_e32 v104, v0
	v_mov_b32_e32 v105, v0
	v_mov_b32_e32 v114, v0
	v_mov_b32_e32 v115, v0
	v_mov_b32_e32 v116, v0
	v_mov_b32_e32 v117, v0
	v_mov_b32_e32 v118, v0
	v_mov_b32_e32 v119, v0
	v_mov_b32_e32 v120, v0
	v_mov_b32_e32 v121, v0
	v_mov_b32_e32 v74, v0
	v_mov_b32_e32 v75, v0
	v_mov_b32_e32 v76, v0
	v_mov_b32_e32 v77, v0
	v_mov_b32_e32 v78, v0
	v_mov_b32_e32 v79, v0
	v_mov_b32_e32 v80, v0
	v_mov_b32_e32 v81, v0
	v_mov_b32_e32 v90, v0
	v_mov_b32_e32 v91, v0
	v_mov_b32_e32 v92, v0
	v_mov_b32_e32 v93, v0
	v_mov_b32_e32 v94, v0
	v_mov_b32_e32 v95, v0
	v_mov_b32_e32 v96, v0
	v_mov_b32_e32 v97, v0
	v_mov_b32_e32 v106, v0
	v_mov_b32_e32 v107, v0
	v_mov_b32_e32 v108, v0
	v_mov_b32_e32 v109, v0
	v_mov_b32_e32 v110, v0
	v_mov_b32_e32 v111, v0
	v_mov_b32_e32 v112, v0
	v_mov_b32_e32 v113, v0
	v_mov_b32_e32 v122, v0
	v_mov_b32_e32 v123, v0
	v_mov_b32_e32 v124, v0
	v_mov_b32_e32 v125, v0
	v_mov_b32_e32 v126, v0
	v_mov_b32_e32 v127, v0
	v_mov_b32_e32 v128, v0
	v_mov_b32_e32 v129, v0
	s_add_u32 s6, s60, 0xfffc0080
	s_addc_u32 s20, s61, -1
	s_cmp_eq_u32 s90, 12
	s_cselect_b32 s65, s18, s20
	s_cselect_b32 s64, s33, s6
	s_cselect_b32 s63, s43, s53
	s_cselect_b32 s62, s45, s51
.LBB0_585:
	s_add_i32 s21, 0, 0x10000
	v_add_u32_e32 v48, s21, v175
	s_add_i32 s6, 0, 0x14000
	ds_read_b128 v[142:145], v48
	ds_read_b128 v[146:149], v48 offset:1024
	ds_read_b128 v[150:153], v48 offset:2048
	ds_read_b128 v[156:159], v48 offset:3072
	v_add_u32_e32 v48, s6, v175
	ds_read_b128 v[160:163], v48
	ds_read_b128 v[164:167], v48 offset:1024
	ds_read_b128 v[168:171], v48 offset:2048
	ds_read_b128 v[180:183], v48 offset:3072
	v_lshl_add_u64 v[172:173], s[60:61], 0, v[138:139]
	s_add_i32 m0, s66, 0xc000
	ds_read_b128 v[184:187], v178
	ds_read_b128 v[188:191], v178 offset:1024
	ds_read_b128 v[192:195], v178 offset:2048
	ds_read_b128 v[196:199], v178 offset:3072
	ds_read_b128 v[200:203], v178 offset:4096
	ds_read_b128 v[216:219], v178 offset:5120
	ds_read_b128 v[220:223], v178 offset:6144
	ds_read_b128 v[224:227], v178 offset:7168
	global_load_lds_dwordx4 v[172:173], off
	v_lshl_add_u64 v[172:173], s[60:61], 0, v[140:141]
	s_add_i32 m0, s66, 0xe000
	s_nop 0
	global_load_lds_dwordx4 v[172:173], off
	s_waitcnt vmcnt(8)
	s_waitcnt lgkmcnt(0)
	s_barrier
	s_setprio 1
	v_mfma_f32_16x16x32_bf16 v[126:129], v[142:145], v[184:187], v[126:129]
	v_mfma_f32_16x16x32_bf16 v[122:125], v[150:153], v[184:187], v[122:125]
	v_mfma_f32_16x16x32_bf16 v[110:113], v[142:145], v[192:195], v[110:113]
	v_mfma_f32_16x16x32_bf16 v[106:109], v[150:153], v[192:195], v[106:109]
	v_mfma_f32_16x16x32_bf16 v[94:97], v[142:145], v[200:203], v[94:97]
	v_mfma_f32_16x16x32_bf16 v[90:93], v[150:153], v[200:203], v[90:93]
	v_mfma_f32_16x16x32_bf16 v[78:81], v[142:145], v[220:223], v[78:81]
	v_mfma_f32_16x16x32_bf16 v[74:77], v[150:153], v[220:223], v[74:77]
	v_mfma_f32_16x16x32_bf16 v[126:129], v[146:149], v[188:191], v[126:129]
	v_mfma_f32_16x16x32_bf16 v[122:125], v[156:159], v[188:191], v[122:125]
	v_mfma_f32_16x16x32_bf16 v[110:113], v[146:149], v[196:199], v[110:113]
	v_mfma_f32_16x16x32_bf16 v[106:109], v[156:159], v[196:199], v[106:109]
	v_mfma_f32_16x16x32_bf16 v[94:97], v[146:149], v[216:219], v[94:97]
	v_mfma_f32_16x16x32_bf16 v[90:93], v[156:159], v[216:219], v[90:93]
	v_mfma_f32_16x16x32_bf16 v[78:81], v[146:149], v[224:227], v[78:81]
	v_mfma_f32_16x16x32_bf16 v[74:77], v[156:159], v[224:227], v[74:77]
	v_mfma_f32_16x16x32_bf16 v[118:121], v[160:163], v[184:187], v[118:121]
	v_mfma_f32_16x16x32_bf16 v[114:117], v[168:171], v[184:187], v[114:117]
	v_mfma_f32_16x16x32_bf16 v[102:105], v[160:163], v[192:195], v[102:105]
	v_mfma_f32_16x16x32_bf16 v[98:101], v[168:171], v[192:195], v[98:101]
	v_mfma_f32_16x16x32_bf16 v[86:89], v[160:163], v[200:203], v[86:89]
	v_mfma_f32_16x16x32_bf16 v[82:85], v[168:171], v[200:203], v[82:85]
	v_mfma_f32_16x16x32_bf16 v[70:73], v[160:163], v[220:223], v[70:73]
	v_mfma_f32_16x16x32_bf16 v[66:69], v[168:171], v[220:223], v[66:69]
	v_mfma_f32_16x16x32_bf16 v[118:121], v[164:167], v[188:191], v[118:121]
	v_mfma_f32_16x16x32_bf16 v[114:117], v[180:183], v[188:191], v[114:117]
	v_mfma_f32_16x16x32_bf16 v[102:105], v[164:167], v[196:199], v[102:105]
	v_mfma_f32_16x16x32_bf16 v[98:101], v[180:183], v[196:199], v[98:101]
	v_mfma_f32_16x16x32_bf16 v[86:89], v[164:167], v[216:219], v[86:89]
	v_mfma_f32_16x16x32_bf16 v[82:85], v[180:183], v[216:219], v[82:85]
	v_mfma_f32_16x16x32_bf16 v[70:73], v[164:167], v[224:227], v[70:73]
	v_mfma_f32_16x16x32_bf16 v[66:69], v[180:183], v[224:227], v[66:69]
	s_setprio 0
	s_barrier
	s_add_i32 s20, s21, s24
	v_lshl_add_u64 v[172:173], s[62:63], 0, v[132:133]
	s_mov_b32 m0, s20
	ds_read_b128 v[184:187], v178 offset:16384
	ds_read_b128 v[188:191], v178 offset:17408
	ds_read_b128 v[192:195], v178 offset:18432
	ds_read_b128 v[196:199], v178 offset:19456
	ds_read_b128 v[200:203], v178 offset:20480
	ds_read_b128 v[216:219], v178 offset:21504
	ds_read_b128 v[220:223], v178 offset:22528
	ds_read_b128 v[224:227], v178 offset:23552
	global_load_lds_dwordx4 v[172:173], off
	s_add_i32 m0, s20, 0x2000
	s_add_u32 s20, s62, 0x40000
	v_lshl_add_u64 v[228:229], s[62:63], 0, v[136:137]
	s_addc_u32 s21, s63, 0
	s_add_i32 s6, s6, s24
	global_load_lds_dwordx4 v[228:229], off
	v_lshl_add_u64 v[230:231], s[20:21], 0, v[132:133]
	s_mov_b32 m0, s6
	v_lshl_add_u64 v[232:233], s[64:65], 0, v[134:135]
	global_load_lds_dwordx4 v[230:231], off
	v_lshl_add_u64 v[230:231], s[20:21], 0, v[136:137]
	s_add_i32 m0, s6, 0x2000
	s_nop 0
	global_load_lds_dwordx4 v[230:231], off
	v_lshl_add_u64 v[230:231], s[64:65], 0, v[130:131]
	s_mov_b32 m0, s66
	s_nop 0
	global_load_lds_dwordx4 v[230:231], off
	s_mov_b32 m0, s67
	s_nop 0
	global_load_lds_dwordx4 v[232:233], off
	s_waitcnt vmcnt(8)
	s_waitcnt lgkmcnt(0)
	s_barrier
	s_setprio 1
	v_mfma_f32_16x16x32_bf16 v[62:65], v[142:145], v[184:187], v[62:65]
	v_mfma_f32_16x16x32_bf16 v[58:61], v[150:153], v[184:187], v[58:61]
	v_mfma_f32_16x16x32_bf16 v[44:47], v[142:145], v[192:195], v[44:47]
	v_mfma_f32_16x16x32_bf16 v[40:43], v[150:153], v[192:195], v[40:43]
	v_mfma_f32_16x16x32_bf16 v[28:31], v[142:145], v[200:203], v[28:31]
	v_mfma_f32_16x16x32_bf16 v[24:27], v[150:153], v[200:203], v[24:27]
	v_mfma_f32_16x16x32_bf16 v[12:15], v[142:145], v[220:223], v[12:15]
	v_mfma_f32_16x16x32_bf16 v[8:11], v[150:153], v[220:223], v[8:11]
	v_mfma_f32_16x16x32_bf16 v[62:65], v[146:149], v[188:191], v[62:65]
	v_mfma_f32_16x16x32_bf16 v[58:61], v[156:159], v[188:191], v[58:61]
	v_mfma_f32_16x16x32_bf16 v[44:47], v[146:149], v[196:199], v[44:47]
	v_mfma_f32_16x16x32_bf16 v[40:43], v[156:159], v[196:199], v[40:43]
	v_mfma_f32_16x16x32_bf16 v[28:31], v[146:149], v[216:219], v[28:31]
	v_mfma_f32_16x16x32_bf16 v[24:27], v[156:159], v[216:219], v[24:27]
	v_mfma_f32_16x16x32_bf16 v[12:15], v[146:149], v[224:227], v[12:15]
	v_mfma_f32_16x16x32_bf16 v[8:11], v[156:159], v[224:227], v[8:11]
	v_mfma_f32_16x16x32_bf16 v[54:57], v[160:163], v[184:187], v[54:57]
	v_mfma_f32_16x16x32_bf16 v[50:53], v[168:171], v[184:187], v[50:53]
	v_mfma_f32_16x16x32_bf16 v[36:39], v[160:163], v[192:195], v[36:39]
	v_mfma_f32_16x16x32_bf16 v[32:35], v[168:171], v[192:195], v[32:35]
	v_mfma_f32_16x16x32_bf16 v[20:23], v[160:163], v[200:203], v[20:23]
	v_mfma_f32_16x16x32_bf16 v[16:19], v[168:171], v[200:203], v[16:19]
	v_mfma_f32_16x16x32_bf16 v[4:7], v[160:163], v[220:223], v[4:7]
	v_mfma_f32_16x16x32_bf16 v[0:3], v[168:171], v[220:223], v[0:3]
	v_mfma_f32_16x16x32_bf16 v[54:57], v[164:167], v[188:191], v[54:57]
	v_mfma_f32_16x16x32_bf16 v[50:53], v[180:183], v[188:191], v[50:53]
	v_mfma_f32_16x16x32_bf16 v[36:39], v[164:167], v[196:199], v[36:39]
	v_mfma_f32_16x16x32_bf16 v[32:35], v[180:183], v[196:199], v[32:35]
	v_mfma_f32_16x16x32_bf16 v[20:23], v[164:167], v[216:219], v[20:23]
	v_mfma_f32_16x16x32_bf16 v[16:19], v[180:183], v[216:219], v[16:19]
	v_mfma_f32_16x16x32_bf16 v[4:7], v[164:167], v[224:227], v[4:7]
	v_mfma_f32_16x16x32_bf16 v[0:3], v[180:183], v[224:227], v[0:3]
	s_setprio 0
	s_barrier
	s_add_i32 s6, 0, 0x18000
	v_add_u32_e32 v48, s6, v175
	s_add_i32 s26, 0, 0x1c000
	ds_read_b128 v[142:145], v48
	ds_read_b128 v[146:149], v48 offset:1024
	ds_read_b128 v[150:153], v48 offset:2048
	ds_read_b128 v[156:159], v48 offset:3072
	v_add_u32_e32 v48, s26, v175
	ds_read_b128 v[160:163], v48
	ds_read_b128 v[164:167], v48 offset:1024
	ds_read_b128 v[168:171], v48 offset:2048
	ds_read_b128 v[180:183], v48 offset:3072
	s_add_u32 s20, s64, 0x40000
	s_addc_u32 s21, s65, 0
	s_mov_b32 m0, s68
	v_lshl_add_u64 v[234:235], s[20:21], 0, v[130:131]
	ds_read_b128 v[184:187], v178 offset:32768
	ds_read_b128 v[188:191], v178 offset:33792
	ds_read_b128 v[192:195], v178 offset:34816
	ds_read_b128 v[196:199], v178 offset:35840
	ds_read_b128 v[200:203], v178 offset:36864
	ds_read_b128 v[216:219], v178 offset:37888
	ds_read_b128 v[220:223], v178 offset:38912
	ds_read_b128 v[224:227], v178 offset:39936
	global_load_lds_dwordx4 v[234:235], off
	v_lshl_add_u64 v[234:235], s[20:21], 0, v[134:135]
	s_mov_b32 m0, s69
	s_nop 0
	global_load_lds_dwordx4 v[234:235], off
	s_waitcnt vmcnt(8)
	s_waitcnt lgkmcnt(0)
	s_barrier
	s_setprio 1
	v_mfma_f32_16x16x32_bf16 v[126:129], v[142:145], v[184:187], v[126:129]
	v_mfma_f32_16x16x32_bf16 v[122:125], v[150:153], v[184:187], v[122:125]
	v_mfma_f32_16x16x32_bf16 v[110:113], v[142:145], v[192:195], v[110:113]
	v_mfma_f32_16x16x32_bf16 v[106:109], v[150:153], v[192:195], v[106:109]
	v_mfma_f32_16x16x32_bf16 v[94:97], v[142:145], v[200:203], v[94:97]
	v_mfma_f32_16x16x32_bf16 v[90:93], v[150:153], v[200:203], v[90:93]
	v_mfma_f32_16x16x32_bf16 v[78:81], v[142:145], v[220:223], v[78:81]
	v_mfma_f32_16x16x32_bf16 v[74:77], v[150:153], v[220:223], v[74:77]
	v_mfma_f32_16x16x32_bf16 v[126:129], v[146:149], v[188:191], v[126:129]
	v_mfma_f32_16x16x32_bf16 v[122:125], v[156:159], v[188:191], v[122:125]
	v_mfma_f32_16x16x32_bf16 v[110:113], v[146:149], v[196:199], v[110:113]
	v_mfma_f32_16x16x32_bf16 v[106:109], v[156:159], v[196:199], v[106:109]
	v_mfma_f32_16x16x32_bf16 v[94:97], v[146:149], v[216:219], v[94:97]
	v_mfma_f32_16x16x32_bf16 v[90:93], v[156:159], v[216:219], v[90:93]
	v_mfma_f32_16x16x32_bf16 v[78:81], v[146:149], v[224:227], v[78:81]
	v_mfma_f32_16x16x32_bf16 v[74:77], v[156:159], v[224:227], v[74:77]
	v_mfma_f32_16x16x32_bf16 v[118:121], v[160:163], v[184:187], v[118:121]
	v_mfma_f32_16x16x32_bf16 v[114:117], v[168:171], v[184:187], v[114:117]
	v_mfma_f32_16x16x32_bf16 v[102:105], v[160:163], v[192:195], v[102:105]
	v_mfma_f32_16x16x32_bf16 v[98:101], v[168:171], v[192:195], v[98:101]
	v_mfma_f32_16x16x32_bf16 v[86:89], v[160:163], v[200:203], v[86:89]
	v_mfma_f32_16x16x32_bf16 v[82:85], v[168:171], v[200:203], v[82:85]
	v_mfma_f32_16x16x32_bf16 v[70:73], v[160:163], v[220:223], v[70:73]
	v_mfma_f32_16x16x32_bf16 v[66:69], v[168:171], v[220:223], v[66:69]
	v_mfma_f32_16x16x32_bf16 v[118:121], v[164:167], v[188:191], v[118:121]
	v_mfma_f32_16x16x32_bf16 v[114:117], v[180:183], v[188:191], v[114:117]
	v_mfma_f32_16x16x32_bf16 v[102:105], v[164:167], v[196:199], v[102:105]
	v_mfma_f32_16x16x32_bf16 v[98:101], v[180:183], v[196:199], v[98:101]
	v_mfma_f32_16x16x32_bf16 v[86:89], v[164:167], v[216:219], v[86:89]
	v_mfma_f32_16x16x32_bf16 v[82:85], v[180:183], v[216:219], v[82:85]
	v_mfma_f32_16x16x32_bf16 v[70:73], v[164:167], v[224:227], v[70:73]
	v_mfma_f32_16x16x32_bf16 v[66:69], v[180:183], v[224:227], v[66:69]
	s_setprio 0
	s_barrier
	s_add_i32 s6, s6, s24
	v_lshl_add_u64 v[172:173], v[172:173], 0, s[30:31]
	s_mov_b32 m0, s6
	ds_read_b128 v[184:187], v178 offset:49152
	ds_read_b128 v[188:191], v178 offset:50176
	ds_read_b128 v[192:195], v178 offset:51200
	ds_read_b128 v[196:199], v178 offset:52224
	ds_read_b128 v[200:203], v178 offset:53248
	ds_read_b128 v[216:219], v178 offset:54272
	ds_read_b128 v[220:223], v178 offset:55296
	ds_read_b128 v[224:227], v178 offset:56320
	global_load_lds_dwordx4 v[172:173], off
	s_add_i32 m0, s6, 0x2000
	s_add_u32 s20, s62, 0x40080
	v_lshl_add_u64 v[172:173], v[228:229], 0, s[30:31]
	s_addc_u32 s21, s63, 0
	s_add_i32 s6, s26, s24
	global_load_lds_dwordx4 v[172:173], off
	v_lshl_add_u64 v[172:173], s[20:21], 0, v[132:133]
	s_mov_b32 m0, s6
	s_nop 0
	global_load_lds_dwordx4 v[172:173], off
	v_lshl_add_u64 v[172:173], s[20:21], 0, v[136:137]
	s_add_i32 m0, s6, 0x2000
	s_nop 0
	global_load_lds_dwordx4 v[172:173], off
	v_lshl_add_u64 v[172:173], v[230:231], 0, s[30:31]
	s_mov_b32 m0, s70
	s_nop 0
	global_load_lds_dwordx4 v[172:173], off
	v_lshl_add_u64 v[172:173], v[232:233], 0, s[30:31]
	s_mov_b32 m0, s71
	s_nop 0
	global_load_lds_dwordx4 v[172:173], off
	s_waitcnt vmcnt(8)
	s_waitcnt lgkmcnt(0)
	s_barrier
	s_setprio 1
	v_mfma_f32_16x16x32_bf16 v[62:65], v[142:145], v[184:187], v[62:65]
	v_mfma_f32_16x16x32_bf16 v[58:61], v[150:153], v[184:187], v[58:61]
	v_mfma_f32_16x16x32_bf16 v[44:47], v[142:145], v[192:195], v[44:47]
	v_mfma_f32_16x16x32_bf16 v[40:43], v[150:153], v[192:195], v[40:43]
	v_mfma_f32_16x16x32_bf16 v[28:31], v[142:145], v[200:203], v[28:31]
	v_mfma_f32_16x16x32_bf16 v[24:27], v[150:153], v[200:203], v[24:27]
	v_mfma_f32_16x16x32_bf16 v[12:15], v[142:145], v[220:223], v[12:15]
	v_mfma_f32_16x16x32_bf16 v[8:11], v[150:153], v[220:223], v[8:11]
	v_mfma_f32_16x16x32_bf16 v[62:65], v[146:149], v[188:191], v[62:65]
	v_mfma_f32_16x16x32_bf16 v[58:61], v[156:159], v[188:191], v[58:61]
	v_mfma_f32_16x16x32_bf16 v[44:47], v[146:149], v[196:199], v[44:47]
	v_mfma_f32_16x16x32_bf16 v[40:43], v[156:159], v[196:199], v[40:43]
	v_mfma_f32_16x16x32_bf16 v[28:31], v[146:149], v[216:219], v[28:31]
	v_mfma_f32_16x16x32_bf16 v[24:27], v[156:159], v[216:219], v[24:27]
	v_mfma_f32_16x16x32_bf16 v[12:15], v[146:149], v[224:227], v[12:15]
	v_mfma_f32_16x16x32_bf16 v[8:11], v[156:159], v[224:227], v[8:11]
	v_mfma_f32_16x16x32_bf16 v[54:57], v[160:163], v[184:187], v[54:57]
	v_mfma_f32_16x16x32_bf16 v[50:53], v[168:171], v[184:187], v[50:53]
	v_mfma_f32_16x16x32_bf16 v[36:39], v[160:163], v[192:195], v[36:39]
	v_mfma_f32_16x16x32_bf16 v[32:35], v[168:171], v[192:195], v[32:35]
	v_mfma_f32_16x16x32_bf16 v[20:23], v[160:163], v[200:203], v[20:23]
	v_mfma_f32_16x16x32_bf16 v[16:19], v[168:171], v[200:203], v[16:19]
	v_mfma_f32_16x16x32_bf16 v[4:7], v[160:163], v[220:223], v[4:7]
	v_mfma_f32_16x16x32_bf16 v[0:3], v[168:171], v[220:223], v[0:3]
	v_mfma_f32_16x16x32_bf16 v[54:57], v[164:167], v[188:191], v[54:57]
	v_mfma_f32_16x16x32_bf16 v[50:53], v[180:183], v[188:191], v[50:53]
	v_mfma_f32_16x16x32_bf16 v[36:39], v[164:167], v[196:199], v[36:39]
	v_mfma_f32_16x16x32_bf16 v[32:35], v[180:183], v[196:199], v[32:35]
	v_mfma_f32_16x16x32_bf16 v[20:23], v[164:167], v[216:219], v[20:23]
	v_mfma_f32_16x16x32_bf16 v[16:19], v[180:183], v[216:219], v[16:19]
	v_mfma_f32_16x16x32_bf16 v[4:7], v[164:167], v[224:227], v[4:7]
	v_mfma_f32_16x16x32_bf16 v[0:3], v[180:183], v[224:227], v[0:3]
	s_setprio 0
	s_add_i32 s90, s90, 2
	s_add_u32 s60, s60, 0x100
	s_addc_u32 s61, s61, 0
	s_add_u32 s51, s51, 0x100
	s_addc_u32 s53, s53, 0
	s_add_u32 s6, s60, 0xfffc0080
	s_addc_u32 s20, s61, -1
	s_cmp_eq_u32 s90, 12
	s_cselect_b32 s65, s18, s20
	s_cselect_b32 s64, s33, s6
	s_cselect_b32 s63, s43, s53
	s_cselect_b32 s62, s45, s51
	s_cmp_gt_u32 s90, 13
	s_barrier
	s_cbranch_scc0 .LBB0_585
	s_and_b64 vcc, exec, s[48:49]
	s_cbranch_vccz .LBB0_588
	s_barrier

.LBB0_689:
	s_ashr_i32 s47, s46, 31
	s_lshl_b64 s[20:21], s[46:47], 19
	s_add_u32 s52, s16, s20
	s_addc_u32 s53, s17, s21
	s_and_b64 s[20:21], s[50:51], exec
	s_cselect_b32 s41, s53, s57
	s_cselect_b32 s47, s52, s56
	s_ashr_i32 s49, s48, 31
	s_lshl_b64 s[20:21], s[48:49], 19
	s_add_u32 s54, s8, s20
	s_addc_u32 s55, s9, s21
	s_and_b64 s[20:21], s[50:51], exec
	s_cselect_b32 s49, s55, s59
	s_cselect_b32 s68, s54, s58
	s_add_u32 s56, s56, 0x40080
	s_addc_u32 s57, s57, 0
	s_add_u32 s69, s58, 0x100
	v_mov_b32_e32 v0, 0
	s_addc_u32 s70, s59, 0
	s_mov_b32 s71, -2
	v_mov_b32_e32 v1, v0
	v_mov_b32_e32 v2, v0
	v_mov_b32_e32 v3, v0
	v_mov_b32_e32 v4, v0
	v_mov_b32_e32 v5, v0
	v_mov_b32_e32 v6, v0
	v_mov_b32_e32 v7, v0
	v_mov_b32_e32 v8, v0
	v_mov_b32_e32 v9, v0
	v_mov_b32_e32 v10, v0
	v_mov_b32_e32 v11, v0
	v_mov_b32_e32 v16, v0
	v_mov_b32_e32 v17, v0
	v_mov_b32_e32 v18, v0
	v_mov_b32_e32 v19, v0
	v_mov_b32_e32 v24, v0
	v_mov_b32_e32 v25, v0
	v_mov_b32_e32 v26, v0
	v_mov_b32_e32 v27, v0
	v_mov_b32_e32 v32, v0
	v_mov_b32_e32 v33, v0
	v_mov_b32_e32 v34, v0
	v_mov_b32_e32 v35, v0
	v_mov_b32_e32 v40, v0
	v_mov_b32_e32 v41, v0
	v_mov_b32_e32 v42, v0
	v_mov_b32_e32 v43, v0
	v_mov_b32_e32 v50, v0
	v_mov_b32_e32 v51, v0
	v_mov_b32_e32 v52, v0
	v_mov_b32_e32 v53, v0
	v_mov_b32_e32 v12, v0
	v_mov_b32_e32 v13, v0
	v_mov_b32_e32 v14, v0
	v_mov_b32_e32 v15, v0
	v_mov_b32_e32 v20, v0
	v_mov_b32_e32 v21, v0
	v_mov_b32_e32 v22, v0
	v_mov_b32_e32 v23, v0
	v_mov_b32_e32 v28, v0
	v_mov_b32_e32 v29, v0
	v_mov_b32_e32 v30, v0
	v_mov_b32_e32 v31, v0
	v_mov_b32_e32 v36, v0
	v_mov_b32_e32 v37, v0
	v_mov_b32_e32 v38, v0
	v_mov_b32_e32 v39, v0
	v_mov_b32_e32 v44, v0
	v_mov_b32_e32 v45, v0
	v_mov_b32_e32 v46, v0
	v_mov_b32_e32 v47, v0
	v_mov_b32_e32 v54, v0
	v_mov_b32_e32 v55, v0
	v_mov_b32_e32 v56, v0
	v_mov_b32_e32 v57, v0
	v_mov_b32_e32 v58, v0
	v_mov_b32_e32 v59, v0
	v_mov_b32_e32 v60, v0
	v_mov_b32_e32 v61, v0
	v_mov_b32_e32 v62, v0
	v_mov_b32_e32 v63, v0
	v_mov_b32_e32 v64, v0
	v_mov_b32_e32 v65, v0
	v_mov_b32_e32 v66, v0
	v_mov_b32_e32 v67, v0
	v_mov_b32_e32 v68, v0
	v_mov_b32_e32 v69, v0
	v_mov_b32_e32 v70, v0
	v_mov_b32_e32 v71, v0
	v_mov_b32_e32 v72, v0
	v_mov_b32_e32 v73, v0
	v_mov_b32_e32 v74, v0
	v_mov_b32_e32 v75, v0
	v_mov_b32_e32 v76, v0
	v_mov_b32_e32 v77, v0
	v_mov_b32_e32 v82, v0
	v_mov_b32_e32 v83, v0
	v_mov_b32_e32 v84, v0
	v_mov_b32_e32 v85, v0
	v_mov_b32_e32 v90, v0
	v_mov_b32_e32 v91, v0
	v_mov_b32_e32 v92, v0
	v_mov_b32_e32 v93, v0
	v_mov_b32_e32 v98, v0
	v_mov_b32_e32 v99, v0
	v_mov_b32_e32 v100, v0
	v_mov_b32_e32 v101, v0
	v_mov_b32_e32 v106, v0
	v_mov_b32_e32 v107, v0
	v_mov_b32_e32 v108, v0
	v_mov_b32_e32 v109, v0
	v_mov_b32_e32 v114, v0
	v_mov_b32_e32 v115, v0
	v_mov_b32_e32 v116, v0
	v_mov_b32_e32 v117, v0
	v_mov_b32_e32 v78, v0
	v_mov_b32_e32 v79, v0
	v_mov_b32_e32 v80, v0
	v_mov_b32_e32 v81, v0
	v_mov_b32_e32 v86, v0
	v_mov_b32_e32 v87, v0
	v_mov_b32_e32 v88, v0
	v_mov_b32_e32 v89, v0
	v_mov_b32_e32 v94, v0
	v_mov_b32_e32 v95, v0
	v_mov_b32_e32 v96, v0
	v_mov_b32_e32 v97, v0
	v_mov_b32_e32 v102, v0
	v_mov_b32_e32 v103, v0
	v_mov_b32_e32 v104, v0
	v_mov_b32_e32 v105, v0
	v_mov_b32_e32 v110, v0
	v_mov_b32_e32 v111, v0
	v_mov_b32_e32 v112, v0
	v_mov_b32_e32 v113, v0
	v_mov_b32_e32 v118, v0
	v_mov_b32_e32 v119, v0
	v_mov_b32_e32 v120, v0
	v_mov_b32_e32 v121, v0
	v_mov_b32_e32 v122, v0
	v_mov_b32_e32 v123, v0
	v_mov_b32_e32 v124, v0
	v_mov_b32_e32 v125, v0
	v_mov_b32_e32 v126, v0
	v_mov_b32_e32 v127, v0
	v_mov_b32_e32 v128, v0
	v_mov_b32_e32 v129, v0
	s_add_u32 s6, s56, 0xfffc0080
	s_addc_u32 s20, s57, -1
	s_cmp_eq_u32 s71, 12
	s_cselect_b32 s61, s41, s20
	s_cselect_b32 s60, s47, s6
	s_cselect_b32 s59, s49, s70
	s_cselect_b32 s58, s68, s69
.LBB0_690:
	s_add_i32 s21, 0, 0x10000
	v_add_u32_e32 v48, s21, v177
	s_add_i32 s6, 0, 0x14000
	ds_read_b128 v[142:145], v48
	ds_read_b128 v[146:149], v48 offset:1024
	ds_read_b128 v[150:153], v48 offset:2048
	ds_read_b128 v[156:159], v48 offset:3072
	v_add_u32_e32 v48, s6, v177
	ds_read_b128 v[160:163], v48
	ds_read_b128 v[164:167], v48 offset:1024
	ds_read_b128 v[168:171], v48 offset:2048
	ds_read_b128 v[172:175], v48 offset:3072
	v_lshl_add_u64 v[202:203], s[56:57], 0, v[138:139]
	s_add_i32 m0, s63, 0xc000
	ds_read_b128 v[182:185], v180
	ds_read_b128 v[186:189], v180 offset:1024
	ds_read_b128 v[190:193], v180 offset:2048
	ds_read_b128 v[194:197], v180 offset:3072
	ds_read_b128 v[198:201], v180 offset:4096
	ds_read_b128 v[216:219], v180 offset:5120
	ds_read_b128 v[220:223], v180 offset:6144
	ds_read_b128 v[224:227], v180 offset:7168
	global_load_lds_dwordx4 v[202:203], off
	v_lshl_add_u64 v[202:203], s[56:57], 0, v[140:141]
	s_add_i32 m0, s63, 0xe000
	s_nop 0
	global_load_lds_dwordx4 v[202:203], off
	s_waitcnt vmcnt(8)
	s_waitcnt lgkmcnt(0)
	s_barrier
	s_setprio 1
	v_mfma_f32_16x16x32_bf16 v[126:129], v[142:145], v[182:185], v[126:129]
	v_mfma_f32_16x16x32_bf16 v[122:125], v[150:153], v[182:185], v[122:125]
	v_mfma_f32_16x16x32_bf16 v[118:121], v[142:145], v[190:193], v[118:121]
	v_mfma_f32_16x16x32_bf16 v[110:113], v[150:153], v[190:193], v[110:113]
	v_mfma_f32_16x16x32_bf16 v[102:105], v[142:145], v[198:201], v[102:105]
	v_mfma_f32_16x16x32_bf16 v[94:97], v[150:153], v[198:201], v[94:97]
	v_mfma_f32_16x16x32_bf16 v[86:89], v[142:145], v[220:223], v[86:89]
	v_mfma_f32_16x16x32_bf16 v[78:81], v[150:153], v[220:223], v[78:81]
	v_mfma_f32_16x16x32_bf16 v[126:129], v[146:149], v[186:189], v[126:129]
	v_mfma_f32_16x16x32_bf16 v[122:125], v[156:159], v[186:189], v[122:125]
	v_mfma_f32_16x16x32_bf16 v[118:121], v[146:149], v[194:197], v[118:121]
	v_mfma_f32_16x16x32_bf16 v[110:113], v[156:159], v[194:197], v[110:113]
	v_mfma_f32_16x16x32_bf16 v[102:105], v[146:149], v[216:219], v[102:105]
	v_mfma_f32_16x16x32_bf16 v[94:97], v[156:159], v[216:219], v[94:97]
	v_mfma_f32_16x16x32_bf16 v[86:89], v[146:149], v[224:227], v[86:89]
	v_mfma_f32_16x16x32_bf16 v[78:81], v[156:159], v[224:227], v[78:81]
	v_mfma_f32_16x16x32_bf16 v[114:117], v[160:163], v[182:185], v[114:117]
	v_mfma_f32_16x16x32_bf16 v[106:109], v[168:171], v[182:185], v[106:109]
	v_mfma_f32_16x16x32_bf16 v[98:101], v[160:163], v[190:193], v[98:101]
	v_mfma_f32_16x16x32_bf16 v[90:93], v[168:171], v[190:193], v[90:93]
	v_mfma_f32_16x16x32_bf16 v[82:85], v[160:163], v[198:201], v[82:85]
	v_mfma_f32_16x16x32_bf16 v[74:77], v[168:171], v[198:201], v[74:77]
	v_mfma_f32_16x16x32_bf16 v[70:73], v[160:163], v[220:223], v[70:73]
	v_mfma_f32_16x16x32_bf16 v[66:69], v[168:171], v[220:223], v[66:69]
	v_mfma_f32_16x16x32_bf16 v[114:117], v[164:167], v[186:189], v[114:117]
	v_mfma_f32_16x16x32_bf16 v[106:109], v[172:175], v[186:189], v[106:109]
	v_mfma_f32_16x16x32_bf16 v[98:101], v[164:167], v[194:197], v[98:101]
	v_mfma_f32_16x16x32_bf16 v[90:93], v[172:175], v[194:197], v[90:93]
	v_mfma_f32_16x16x32_bf16 v[82:85], v[164:167], v[216:219], v[82:85]
	v_mfma_f32_16x16x32_bf16 v[74:77], v[172:175], v[216:219], v[74:77]
	v_mfma_f32_16x16x32_bf16 v[70:73], v[164:167], v[224:227], v[70:73]
	v_mfma_f32_16x16x32_bf16 v[66:69], v[172:175], v[224:227], v[66:69]
	s_setprio 0
	s_barrier
	s_add_i32 s20, s21, s62
	v_lshl_add_u64 v[202:203], s[58:59], 0, v[134:135]
	s_mov_b32 m0, s20
	ds_read_b128 v[182:185], v180 offset:16384
	ds_read_b128 v[186:189], v180 offset:17408
	ds_read_b128 v[190:193], v180 offset:18432
	ds_read_b128 v[194:197], v180 offset:19456
	ds_read_b128 v[198:201], v180 offset:20480
	ds_read_b128 v[216:219], v180 offset:21504
	ds_read_b128 v[220:223], v180 offset:22528
	ds_read_b128 v[224:227], v180 offset:23552
	global_load_lds_dwordx4 v[202:203], off
	s_add_i32 m0, s20, 0x2000
	s_add_u32 s20, s58, 0x40000
	v_lshl_add_u64 v[228:229], s[58:59], 0, v[130:131]
	s_addc_u32 s21, s59, 0
	s_add_i32 s6, s6, s62
	global_load_lds_dwordx4 v[228:229], off
	v_lshl_add_u64 v[230:231], s[20:21], 0, v[134:135]
	s_mov_b32 m0, s6
	v_lshl_add_u64 v[232:233], s[60:61], 0, v[132:133]
	global_load_lds_dwordx4 v[230:231], off
	v_lshl_add_u64 v[230:231], s[20:21], 0, v[130:131]
	s_add_i32 m0, s6, 0x2000
	s_nop 0
	global_load_lds_dwordx4 v[230:231], off
	v_lshl_add_u64 v[230:231], s[60:61], 0, v[136:137]
	s_mov_b32 m0, s63
	s_nop 0
	global_load_lds_dwordx4 v[230:231], off
	s_mov_b32 m0, s64
	s_nop 0
	global_load_lds_dwordx4 v[232:233], off
	s_waitcnt vmcnt(8)
	s_waitcnt lgkmcnt(0)
	s_barrier
	s_setprio 1
	v_mfma_f32_16x16x32_bf16 v[62:65], v[142:145], v[182:185], v[62:65]
	v_mfma_f32_16x16x32_bf16 v[58:61], v[150:153], v[182:185], v[58:61]
	v_mfma_f32_16x16x32_bf16 v[54:57], v[142:145], v[190:193], v[54:57]
	v_mfma_f32_16x16x32_bf16 v[44:47], v[150:153], v[190:193], v[44:47]
	v_mfma_f32_16x16x32_bf16 v[36:39], v[142:145], v[198:201], v[36:39]
	v_mfma_f32_16x16x32_bf16 v[28:31], v[150:153], v[198:201], v[28:31]
	v_mfma_f32_16x16x32_bf16 v[20:23], v[142:145], v[220:223], v[20:23]
	v_mfma_f32_16x16x32_bf16 v[12:15], v[150:153], v[220:223], v[12:15]
	v_mfma_f32_16x16x32_bf16 v[62:65], v[146:149], v[186:189], v[62:65]
	v_mfma_f32_16x16x32_bf16 v[58:61], v[156:159], v[186:189], v[58:61]
	v_mfma_f32_16x16x32_bf16 v[54:57], v[146:149], v[194:197], v[54:57]
	v_mfma_f32_16x16x32_bf16 v[44:47], v[156:159], v[194:197], v[44:47]
	v_mfma_f32_16x16x32_bf16 v[36:39], v[146:149], v[216:219], v[36:39]
	v_mfma_f32_16x16x32_bf16 v[28:31], v[156:159], v[216:219], v[28:31]
	v_mfma_f32_16x16x32_bf16 v[20:23], v[146:149], v[224:227], v[20:23]
	v_mfma_f32_16x16x32_bf16 v[12:15], v[156:159], v[224:227], v[12:15]
	v_mfma_f32_16x16x32_bf16 v[50:53], v[160:163], v[182:185], v[50:53]
	v_mfma_f32_16x16x32_bf16 v[40:43], v[168:171], v[182:185], v[40:43]
	v_mfma_f32_16x16x32_bf16 v[32:35], v[160:163], v[190:193], v[32:35]
	v_mfma_f32_16x16x32_bf16 v[24:27], v[168:171], v[190:193], v[24:27]
	v_mfma_f32_16x16x32_bf16 v[16:19], v[160:163], v[198:201], v[16:19]
	v_mfma_f32_16x16x32_bf16 v[8:11], v[168:171], v[198:201], v[8:11]
	v_mfma_f32_16x16x32_bf16 v[4:7], v[160:163], v[220:223], v[4:7]
	v_mfma_f32_16x16x32_bf16 v[0:3], v[168:171], v[220:223], v[0:3]
	v_mfma_f32_16x16x32_bf16 v[50:53], v[164:167], v[186:189], v[50:53]
	v_mfma_f32_16x16x32_bf16 v[40:43], v[172:175], v[186:189], v[40:43]
	v_mfma_f32_16x16x32_bf16 v[32:35], v[164:167], v[194:197], v[32:35]
	v_mfma_f32_16x16x32_bf16 v[24:27], v[172:175], v[194:197], v[24:27]
	v_mfma_f32_16x16x32_bf16 v[16:19], v[164:167], v[216:219], v[16:19]
	v_mfma_f32_16x16x32_bf16 v[8:11], v[172:175], v[216:219], v[8:11]
	v_mfma_f32_16x16x32_bf16 v[4:7], v[164:167], v[224:227], v[4:7]
	v_mfma_f32_16x16x32_bf16 v[0:3], v[172:175], v[224:227], v[0:3]
	s_setprio 0
	s_barrier
	s_add_i32 s6, 0, 0x18000
	v_add_u32_e32 v48, s6, v177
	s_add_i32 s26, 0, 0x1c000
	ds_read_b128 v[142:145], v48
	ds_read_b128 v[146:149], v48 offset:1024
	ds_read_b128 v[150:153], v48 offset:2048
	ds_read_b128 v[156:159], v48 offset:3072
	v_add_u32_e32 v48, s26, v177
	ds_read_b128 v[160:163], v48
	ds_read_b128 v[164:167], v48 offset:1024
	ds_read_b128 v[168:171], v48 offset:2048
	ds_read_b128 v[172:175], v48 offset:3072
	s_add_u32 s20, s60, 0x40000
	s_addc_u32 s21, s61, 0
	s_mov_b32 m0, s65
	v_lshl_add_u64 v[234:235], s[20:21], 0, v[136:137]
	ds_read_b128 v[182:185], v180 offset:32768
	ds_read_b128 v[186:189], v180 offset:33792
	ds_read_b128 v[190:193], v180 offset:34816
	ds_read_b128 v[194:197], v180 offset:35840
	ds_read_b128 v[198:201], v180 offset:36864
	ds_read_b128 v[216:219], v180 offset:37888
	ds_read_b128 v[220:223], v180 offset:38912
	ds_read_b128 v[224:227], v180 offset:39936
	global_load_lds_dwordx4 v[234:235], off
	v_lshl_add_u64 v[234:235], s[20:21], 0, v[132:133]
	s_mov_b32 m0, s66
	s_nop 0
	global_load_lds_dwordx4 v[234:235], off
	s_waitcnt vmcnt(8)
	s_waitcnt lgkmcnt(0)
	s_barrier
	s_setprio 1
	v_mfma_f32_16x16x32_bf16 v[126:129], v[142:145], v[182:185], v[126:129]
	v_mfma_f32_16x16x32_bf16 v[122:125], v[150:153], v[182:185], v[122:125]
	v_mfma_f32_16x16x32_bf16 v[118:121], v[142:145], v[190:193], v[118:121]
	v_mfma_f32_16x16x32_bf16 v[110:113], v[150:153], v[190:193], v[110:113]
	v_mfma_f32_16x16x32_bf16 v[102:105], v[142:145], v[198:201], v[102:105]
	v_mfma_f32_16x16x32_bf16 v[94:97], v[150:153], v[198:201], v[94:97]
	v_mfma_f32_16x16x32_bf16 v[86:89], v[142:145], v[220:223], v[86:89]
	v_mfma_f32_16x16x32_bf16 v[78:81], v[150:153], v[220:223], v[78:81]
	v_mfma_f32_16x16x32_bf16 v[126:129], v[146:149], v[186:189], v[126:129]
	v_mfma_f32_16x16x32_bf16 v[122:125], v[156:159], v[186:189], v[122:125]
	v_mfma_f32_16x16x32_bf16 v[118:121], v[146:149], v[194:197], v[118:121]
	v_mfma_f32_16x16x32_bf16 v[110:113], v[156:159], v[194:197], v[110:113]
	v_mfma_f32_16x16x32_bf16 v[102:105], v[146:149], v[216:219], v[102:105]
	v_mfma_f32_16x16x32_bf16 v[94:97], v[156:159], v[216:219], v[94:97]
	v_mfma_f32_16x16x32_bf16 v[86:89], v[146:149], v[224:227], v[86:89]
	v_mfma_f32_16x16x32_bf16 v[78:81], v[156:159], v[224:227], v[78:81]
	v_mfma_f32_16x16x32_bf16 v[114:117], v[160:163], v[182:185], v[114:117]
	v_mfma_f32_16x16x32_bf16 v[106:109], v[168:171], v[182:185], v[106:109]
	v_mfma_f32_16x16x32_bf16 v[98:101], v[160:163], v[190:193], v[98:101]
	v_mfma_f32_16x16x32_bf16 v[90:93], v[168:171], v[190:193], v[90:93]
	v_mfma_f32_16x16x32_bf16 v[82:85], v[160:163], v[198:201], v[82:85]
	v_mfma_f32_16x16x32_bf16 v[74:77], v[168:171], v[198:201], v[74:77]
	v_mfma_f32_16x16x32_bf16 v[70:73], v[160:163], v[220:223], v[70:73]
	v_mfma_f32_16x16x32_bf16 v[66:69], v[168:171], v[220:223], v[66:69]
	v_mfma_f32_16x16x32_bf16 v[114:117], v[164:167], v[186:189], v[114:117]
	v_mfma_f32_16x16x32_bf16 v[106:109], v[172:175], v[186:189], v[106:109]
	v_mfma_f32_16x16x32_bf16 v[98:101], v[164:167], v[194:197], v[98:101]
	v_mfma_f32_16x16x32_bf16 v[90:93], v[172:175], v[194:197], v[90:93]
	v_mfma_f32_16x16x32_bf16 v[82:85], v[164:167], v[216:219], v[82:85]
	v_mfma_f32_16x16x32_bf16 v[74:77], v[172:175], v[216:219], v[74:77]
	v_mfma_f32_16x16x32_bf16 v[70:73], v[164:167], v[224:227], v[70:73]
	v_mfma_f32_16x16x32_bf16 v[66:69], v[172:175], v[224:227], v[66:69]
	s_setprio 0
	s_barrier
	s_add_i32 s6, s6, s62
	v_lshl_add_u64 v[202:203], v[202:203], 0, s[30:31]
	s_mov_b32 m0, s6
	ds_read_b128 v[182:185], v180 offset:49152
	ds_read_b128 v[186:189], v180 offset:50176
	ds_read_b128 v[190:193], v180 offset:51200
	ds_read_b128 v[194:197], v180 offset:52224
	ds_read_b128 v[198:201], v180 offset:53248
	ds_read_b128 v[216:219], v180 offset:54272
	ds_read_b128 v[220:223], v180 offset:55296
	ds_read_b128 v[224:227], v180 offset:56320
	global_load_lds_dwordx4 v[202:203], off
	s_add_i32 m0, s6, 0x2000
	s_add_u32 s20, s58, 0x40080
	v_lshl_add_u64 v[202:203], v[228:229], 0, s[30:31]
	s_addc_u32 s21, s59, 0
	s_add_i32 s6, s26, s62
	global_load_lds_dwordx4 v[202:203], off
	v_lshl_add_u64 v[202:203], s[20:21], 0, v[134:135]
	s_mov_b32 m0, s6
	s_nop 0
	global_load_lds_dwordx4 v[202:203], off
	v_lshl_add_u64 v[202:203], s[20:21], 0, v[130:131]
	s_add_i32 m0, s6, 0x2000
	s_nop 0
	global_load_lds_dwordx4 v[202:203], off
	v_lshl_add_u64 v[202:203], v[230:231], 0, s[30:31]
	s_mov_b32 m0, s18
	s_nop 0
	global_load_lds_dwordx4 v[202:203], off
	v_lshl_add_u64 v[202:203], v[232:233], 0, s[30:31]
	s_mov_b32 m0, s24
	s_nop 0
	global_load_lds_dwordx4 v[202:203], off
	s_waitcnt vmcnt(8)
	s_waitcnt lgkmcnt(0)
	s_barrier
	s_setprio 1
	v_mfma_f32_16x16x32_bf16 v[62:65], v[142:145], v[182:185], v[62:65]
	v_mfma_f32_16x16x32_bf16 v[58:61], v[150:153], v[182:185], v[58:61]
	v_mfma_f32_16x16x32_bf16 v[54:57], v[142:145], v[190:193], v[54:57]
	v_mfma_f32_16x16x32_bf16 v[44:47], v[150:153], v[190:193], v[44:47]
	v_mfma_f32_16x16x32_bf16 v[36:39], v[142:145], v[198:201], v[36:39]
	v_mfma_f32_16x16x32_bf16 v[28:31], v[150:153], v[198:201], v[28:31]
	v_mfma_f32_16x16x32_bf16 v[20:23], v[142:145], v[220:223], v[20:23]
	v_mfma_f32_16x16x32_bf16 v[12:15], v[150:153], v[220:223], v[12:15]
	v_mfma_f32_16x16x32_bf16 v[62:65], v[146:149], v[186:189], v[62:65]
	v_mfma_f32_16x16x32_bf16 v[58:61], v[156:159], v[186:189], v[58:61]
	v_mfma_f32_16x16x32_bf16 v[54:57], v[146:149], v[194:197], v[54:57]
	v_mfma_f32_16x16x32_bf16 v[44:47], v[156:159], v[194:197], v[44:47]
	v_mfma_f32_16x16x32_bf16 v[36:39], v[146:149], v[216:219], v[36:39]
	v_mfma_f32_16x16x32_bf16 v[28:31], v[156:159], v[216:219], v[28:31]
	v_mfma_f32_16x16x32_bf16 v[20:23], v[146:149], v[224:227], v[20:23]
	v_mfma_f32_16x16x32_bf16 v[12:15], v[156:159], v[224:227], v[12:15]
	v_mfma_f32_16x16x32_bf16 v[50:53], v[160:163], v[182:185], v[50:53]
	v_mfma_f32_16x16x32_bf16 v[40:43], v[168:171], v[182:185], v[40:43]
	v_mfma_f32_16x16x32_bf16 v[32:35], v[160:163], v[190:193], v[32:35]
	v_mfma_f32_16x16x32_bf16 v[24:27], v[168:171], v[190:193], v[24:27]
	v_mfma_f32_16x16x32_bf16 v[16:19], v[160:163], v[198:201], v[16:19]
	v_mfma_f32_16x16x32_bf16 v[8:11], v[168:171], v[198:201], v[8:11]
	v_mfma_f32_16x16x32_bf16 v[4:7], v[160:163], v[220:223], v[4:7]
	v_mfma_f32_16x16x32_bf16 v[0:3], v[168:171], v[220:223], v[0:3]
	v_mfma_f32_16x16x32_bf16 v[50:53], v[164:167], v[186:189], v[50:53]
	v_mfma_f32_16x16x32_bf16 v[40:43], v[172:175], v[186:189], v[40:43]
	v_mfma_f32_16x16x32_bf16 v[32:35], v[164:167], v[194:197], v[32:35]
	v_mfma_f32_16x16x32_bf16 v[24:27], v[172:175], v[194:197], v[24:27]
	v_mfma_f32_16x16x32_bf16 v[16:19], v[164:167], v[216:219], v[16:19]
	v_mfma_f32_16x16x32_bf16 v[8:11], v[172:175], v[216:219], v[8:11]
	v_mfma_f32_16x16x32_bf16 v[4:7], v[164:167], v[224:227], v[4:7]
	v_mfma_f32_16x16x32_bf16 v[0:3], v[172:175], v[224:227], v[0:3]
	s_setprio 0
	s_add_i32 s71, s71, 2
	s_add_u32 s56, s56, 0x100
	s_addc_u32 s57, s57, 0
	s_add_u32 s69, s69, 0x100
	s_addc_u32 s70, s70, 0
	s_add_u32 s6, s56, 0xfffc0080
	s_addc_u32 s20, s57, -1
	s_cmp_eq_u32 s71, 12
	s_cselect_b32 s61, s41, s20
	s_cselect_b32 s60, s47, s6
	s_cselect_b32 s59, s49, s70
	s_cselect_b32 s58, s68, s69
	s_cmp_gt_u32 s71, 13
	s_barrier
	s_cbranch_scc0 .LBB0_690
	s_and_b64 vcc, exec, s[44:45]
	s_cbranch_vccz .LBB0_693
	s_barrier

.LBB0_1300:
	s_ashr_i32 s45, s44, 31
	s_lshl_b64 s[20:21], s[44:45], 19
	v_readlane_b32 s26, v255, 35
	v_readlane_b32 s27, v255, 36
	s_add_u32 s48, s26, s20
	s_addc_u32 s49, s27, s21
	s_and_b64 s[20:21], s[42:43], exec
	s_cselect_b32 s18, s49, s57
	s_cselect_b32 s33, s48, s56
	s_ashr_i32 s47, s46, 31
	s_lshl_b64 s[20:21], s[46:47], 19
	s_add_u32 s50, s8, s20
	s_addc_u32 s51, s9, s21
	s_and_b64 s[20:21], s[42:43], exec
	s_cselect_b32 s45, s51, s59
	s_cselect_b32 s47, s50, s58
	s_add_u32 s56, s56, 0x40080
	s_addc_u32 s57, s57, 0
	s_add_u32 s53, s58, 0x100
	v_mov_b32_e32 v0, 0
	s_addc_u32 s69, s59, 0
	s_mov_b32 s70, -2
	v_mov_b32_e32 v1, v0
	v_mov_b32_e32 v2, v0
	v_mov_b32_e32 v3, v0
	v_mov_b32_e32 v4, v0
	v_mov_b32_e32 v5, v0
	v_mov_b32_e32 v6, v0
	v_mov_b32_e32 v7, v0
	v_mov_b32_e32 v16, v0
	v_mov_b32_e32 v17, v0
	v_mov_b32_e32 v18, v0
	v_mov_b32_e32 v19, v0
	v_mov_b32_e32 v20, v0
	v_mov_b32_e32 v21, v0
	v_mov_b32_e32 v22, v0
	v_mov_b32_e32 v23, v0
	v_mov_b32_e32 v32, v0
	v_mov_b32_e32 v33, v0
	v_mov_b32_e32 v34, v0
	v_mov_b32_e32 v35, v0
	v_mov_b32_e32 v36, v0
	v_mov_b32_e32 v37, v0
	v_mov_b32_e32 v38, v0
	v_mov_b32_e32 v39, v0
	v_mov_b32_e32 v50, v0
	v_mov_b32_e32 v51, v0
	v_mov_b32_e32 v52, v0
	v_mov_b32_e32 v53, v0
	v_mov_b32_e32 v54, v0
	v_mov_b32_e32 v55, v0
	v_mov_b32_e32 v56, v0
	v_mov_b32_e32 v57, v0
	v_mov_b32_e32 v8, v0
	v_mov_b32_e32 v9, v0
	v_mov_b32_e32 v10, v0
	v_mov_b32_e32 v11, v0
	v_mov_b32_e32 v12, v0
	v_mov_b32_e32 v13, v0
	v_mov_b32_e32 v14, v0
	v_mov_b32_e32 v15, v0
	v_mov_b32_e32 v24, v0
	v_mov_b32_e32 v25, v0
	v_mov_b32_e32 v26, v0
	v_mov_b32_e32 v27, v0
	v_mov_b32_e32 v28, v0
	v_mov_b32_e32 v29, v0
	v_mov_b32_e32 v30, v0
	v_mov_b32_e32 v31, v0
	v_mov_b32_e32 v40, v0
	v_mov_b32_e32 v41, v0
	v_mov_b32_e32 v42, v0
	v_mov_b32_e32 v43, v0
	v_mov_b32_e32 v44, v0
	v_mov_b32_e32 v45, v0
	v_mov_b32_e32 v46, v0
	v_mov_b32_e32 v47, v0
	v_mov_b32_e32 v58, v0
	v_mov_b32_e32 v59, v0
	v_mov_b32_e32 v60, v0
	v_mov_b32_e32 v61, v0
	v_mov_b32_e32 v62, v0
	v_mov_b32_e32 v63, v0
	v_mov_b32_e32 v64, v0
	v_mov_b32_e32 v65, v0
	v_mov_b32_e32 v66, v0
	v_mov_b32_e32 v67, v0
	v_mov_b32_e32 v68, v0
	v_mov_b32_e32 v69, v0
	v_mov_b32_e32 v70, v0
	v_mov_b32_e32 v71, v0
	v_mov_b32_e32 v72, v0
	v_mov_b32_e32 v73, v0
	v_mov_b32_e32 v82, v0
	v_mov_b32_e32 v83, v0
	v_mov_b32_e32 v84, v0
	v_mov_b32_e32 v85, v0
	v_mov_b32_e32 v86, v0
	v_mov_b32_e32 v87, v0
	v_mov_b32_e32 v88, v0
	v_mov_b32_e32 v89, v0
	v_mov_b32_e32 v98, v0
	v_mov_b32_e32 v99, v0
	v_mov_b32_e32 v100, v0
	v_mov_b32_e32 v101, v0
	v_mov_b32_e32 v102, v0
	v_mov_b32_e32 v103, v0
	v_mov_b32_e32 v104, v0
	v_mov_b32_e32 v105, v0
	v_mov_b32_e32 v114, v0
	v_mov_b32_e32 v115, v0
	v_mov_b32_e32 v116, v0
	v_mov_b32_e32 v117, v0
	v_mov_b32_e32 v118, v0
	v_mov_b32_e32 v119, v0
	v_mov_b32_e32 v120, v0
	v_mov_b32_e32 v121, v0
	v_mov_b32_e32 v74, v0
	v_mov_b32_e32 v75, v0
	v_mov_b32_e32 v76, v0
	v_mov_b32_e32 v77, v0
	v_mov_b32_e32 v78, v0
	v_mov_b32_e32 v79, v0
	v_mov_b32_e32 v80, v0
	v_mov_b32_e32 v81, v0
	v_mov_b32_e32 v90, v0
	v_mov_b32_e32 v91, v0
	v_mov_b32_e32 v92, v0
	v_mov_b32_e32 v93, v0
	v_mov_b32_e32 v94, v0
	v_mov_b32_e32 v95, v0
	v_mov_b32_e32 v96, v0
	v_mov_b32_e32 v97, v0
	v_mov_b32_e32 v106, v0
	v_mov_b32_e32 v107, v0
	v_mov_b32_e32 v108, v0
	v_mov_b32_e32 v109, v0
	v_mov_b32_e32 v110, v0
	v_mov_b32_e32 v111, v0
	v_mov_b32_e32 v112, v0
	v_mov_b32_e32 v113, v0
	v_mov_b32_e32 v126, v0
	v_mov_b32_e32 v127, v0
	v_mov_b32_e32 v128, v0
	v_mov_b32_e32 v129, v0
	v_mov_b32_e32 v134, v0
	v_mov_b32_e32 v135, v0
	v_mov_b32_e32 v136, v0
	v_mov_b32_e32 v137, v0
	s_add_u32 s6, s56, 0xfffc0080
	s_addc_u32 s20, s57, -1
	s_cmp_eq_u32 s70, 12
	s_cselect_b32 s61, s18, s20
	s_cselect_b32 s60, s33, s6
	s_cselect_b32 s59, s45, s69
	s_cselect_b32 s58, s47, s53
.LBB0_1301:
	s_add_i32 s21, 0, 0x10000
	v_add_u32_e32 v48, s21, v183
	s_add_i32 s6, 0, 0x14000
	ds_read_b128 v[122:125], v48
	ds_read_b128 v[130:133], v48 offset:1024
	ds_read_b128 v[138:141], v48 offset:2048
	ds_read_b128 v[142:145], v48 offset:3072
	v_add_u32_e32 v48, s6, v183
	ds_read_b128 v[146:149], v48
	ds_read_b128 v[150:153], v48 offset:1024
	ds_read_b128 v[168:171], v48 offset:2048
	ds_read_b128 v[172:175], v48 offset:3072
	v_lshl_add_u64 v[180:181], s[56:57], 0, v[164:165]
	s_add_i32 m0, s55, 0xc000
	ds_read_b128 v[176:179], v185
	ds_read_b128 v[186:189], v185 offset:1024
	ds_read_b128 v[190:193], v185 offset:2048
	ds_read_b128 v[194:197], v185 offset:3072
	ds_read_b128 v[198:201], v185 offset:4096
	ds_read_b128 v[216:219], v185 offset:5120
	ds_read_b128 v[220:223], v185 offset:6144
	ds_read_b128 v[224:227], v185 offset:7168
	global_load_lds_dwordx4 v[180:181], off
	v_lshl_add_u64 v[180:181], s[56:57], 0, v[166:167]
	s_add_i32 m0, s55, 0xe000
	s_nop 0
	global_load_lds_dwordx4 v[180:181], off
	s_waitcnt vmcnt(8)
	s_waitcnt lgkmcnt(0)
	s_barrier
	s_setprio 1
	v_mfma_f32_16x16x32_bf16 v[134:137], v[122:125], v[176:179], v[134:137]
	v_mfma_f32_16x16x32_bf16 v[126:129], v[138:141], v[176:179], v[126:129]
	v_mfma_f32_16x16x32_bf16 v[110:113], v[122:125], v[190:193], v[110:113]
	v_mfma_f32_16x16x32_bf16 v[106:109], v[138:141], v[190:193], v[106:109]
	v_mfma_f32_16x16x32_bf16 v[94:97], v[122:125], v[198:201], v[94:97]
	v_mfma_f32_16x16x32_bf16 v[90:93], v[138:141], v[198:201], v[90:93]
	v_mfma_f32_16x16x32_bf16 v[78:81], v[122:125], v[220:223], v[78:81]
	v_mfma_f32_16x16x32_bf16 v[74:77], v[138:141], v[220:223], v[74:77]
	v_mfma_f32_16x16x32_bf16 v[134:137], v[130:133], v[186:189], v[134:137]
	v_mfma_f32_16x16x32_bf16 v[126:129], v[142:145], v[186:189], v[126:129]
	v_mfma_f32_16x16x32_bf16 v[110:113], v[130:133], v[194:197], v[110:113]
	v_mfma_f32_16x16x32_bf16 v[106:109], v[142:145], v[194:197], v[106:109]
	v_mfma_f32_16x16x32_bf16 v[94:97], v[130:133], v[216:219], v[94:97]
	v_mfma_f32_16x16x32_bf16 v[90:93], v[142:145], v[216:219], v[90:93]
	v_mfma_f32_16x16x32_bf16 v[78:81], v[130:133], v[224:227], v[78:81]
	v_mfma_f32_16x16x32_bf16 v[74:77], v[142:145], v[224:227], v[74:77]
	v_mfma_f32_16x16x32_bf16 v[118:121], v[146:149], v[176:179], v[118:121]
	v_mfma_f32_16x16x32_bf16 v[114:117], v[168:171], v[176:179], v[114:117]
	v_mfma_f32_16x16x32_bf16 v[102:105], v[146:149], v[190:193], v[102:105]
	v_mfma_f32_16x16x32_bf16 v[98:101], v[168:171], v[190:193], v[98:101]
	v_mfma_f32_16x16x32_bf16 v[86:89], v[146:149], v[198:201], v[86:89]
	v_mfma_f32_16x16x32_bf16 v[82:85], v[168:171], v[198:201], v[82:85]
	v_mfma_f32_16x16x32_bf16 v[70:73], v[146:149], v[220:223], v[70:73]
	v_mfma_f32_16x16x32_bf16 v[66:69], v[168:171], v[220:223], v[66:69]
	v_mfma_f32_16x16x32_bf16 v[118:121], v[150:153], v[186:189], v[118:121]
	v_mfma_f32_16x16x32_bf16 v[114:117], v[172:175], v[186:189], v[114:117]
	v_mfma_f32_16x16x32_bf16 v[102:105], v[150:153], v[194:197], v[102:105]
	v_mfma_f32_16x16x32_bf16 v[98:101], v[172:175], v[194:197], v[98:101]
	v_mfma_f32_16x16x32_bf16 v[86:89], v[150:153], v[216:219], v[86:89]
	v_mfma_f32_16x16x32_bf16 v[82:85], v[172:175], v[216:219], v[82:85]
	v_mfma_f32_16x16x32_bf16 v[70:73], v[150:153], v[224:227], v[70:73]
	v_mfma_f32_16x16x32_bf16 v[66:69], v[172:175], v[224:227], v[66:69]
	s_setprio 0
	s_barrier
	s_add_i32 s20, s21, s24
	v_lshl_add_u64 v[180:181], s[58:59], 0, v[158:159]
	s_mov_b32 m0, s20
	ds_read_b128 v[176:179], v185 offset:16384
	ds_read_b128 v[186:189], v185 offset:17408
	ds_read_b128 v[190:193], v185 offset:18432
	ds_read_b128 v[194:197], v185 offset:19456
	ds_read_b128 v[198:201], v185 offset:20480
	ds_read_b128 v[216:219], v185 offset:21504
	ds_read_b128 v[220:223], v185 offset:22528
	ds_read_b128 v[224:227], v185 offset:23552
	global_load_lds_dwordx4 v[180:181], off
	s_add_i32 m0, s20, 0x2000
	s_add_u32 s20, s58, 0x40000
	v_lshl_add_u64 v[202:203], s[58:59], 0, v[162:163]
	s_addc_u32 s21, s59, 0
	s_add_i32 s6, s6, s24
	global_load_lds_dwordx4 v[202:203], off
	v_lshl_add_u64 v[212:213], s[20:21], 0, v[158:159]
	s_mov_b32 m0, s6
	v_lshl_add_u64 v[214:215], s[60:61], 0, v[160:161]
	global_load_lds_dwordx4 v[212:213], off
	v_lshl_add_u64 v[212:213], s[20:21], 0, v[162:163]
	s_add_i32 m0, s6, 0x2000
	s_nop 0
	global_load_lds_dwordx4 v[212:213], off
	v_lshl_add_u64 v[212:213], s[60:61], 0, v[156:157]
	s_mov_b32 m0, s55
	s_nop 0
	global_load_lds_dwordx4 v[212:213], off
	s_mov_b32 m0, s62
	s_nop 0
	global_load_lds_dwordx4 v[214:215], off
	s_waitcnt vmcnt(8)
	s_waitcnt lgkmcnt(0)
	s_barrier
	s_setprio 1
	v_mfma_f32_16x16x32_bf16 v[62:65], v[122:125], v[176:179], v[62:65]
	v_mfma_f32_16x16x32_bf16 v[58:61], v[138:141], v[176:179], v[58:61]
	v_mfma_f32_16x16x32_bf16 v[44:47], v[122:125], v[190:193], v[44:47]
	v_mfma_f32_16x16x32_bf16 v[40:43], v[138:141], v[190:193], v[40:43]
	v_mfma_f32_16x16x32_bf16 v[28:31], v[122:125], v[198:201], v[28:31]
	v_mfma_f32_16x16x32_bf16 v[24:27], v[138:141], v[198:201], v[24:27]
	v_mfma_f32_16x16x32_bf16 v[12:15], v[122:125], v[220:223], v[12:15]
	v_mfma_f32_16x16x32_bf16 v[8:11], v[138:141], v[220:223], v[8:11]
	v_mfma_f32_16x16x32_bf16 v[62:65], v[130:133], v[186:189], v[62:65]
	v_mfma_f32_16x16x32_bf16 v[58:61], v[142:145], v[186:189], v[58:61]
	v_mfma_f32_16x16x32_bf16 v[44:47], v[130:133], v[194:197], v[44:47]
	v_mfma_f32_16x16x32_bf16 v[40:43], v[142:145], v[194:197], v[40:43]
	v_mfma_f32_16x16x32_bf16 v[28:31], v[130:133], v[216:219], v[28:31]
	v_mfma_f32_16x16x32_bf16 v[24:27], v[142:145], v[216:219], v[24:27]
	v_mfma_f32_16x16x32_bf16 v[12:15], v[130:133], v[224:227], v[12:15]
	v_mfma_f32_16x16x32_bf16 v[8:11], v[142:145], v[224:227], v[8:11]
	v_mfma_f32_16x16x32_bf16 v[54:57], v[146:149], v[176:179], v[54:57]
	v_mfma_f32_16x16x32_bf16 v[50:53], v[168:171], v[176:179], v[50:53]
	v_mfma_f32_16x16x32_bf16 v[36:39], v[146:149], v[190:193], v[36:39]
	v_mfma_f32_16x16x32_bf16 v[32:35], v[168:171], v[190:193], v[32:35]
	v_mfma_f32_16x16x32_bf16 v[20:23], v[146:149], v[198:201], v[20:23]
	v_mfma_f32_16x16x32_bf16 v[16:19], v[168:171], v[198:201], v[16:19]
	v_mfma_f32_16x16x32_bf16 v[4:7], v[146:149], v[220:223], v[4:7]
	v_mfma_f32_16x16x32_bf16 v[0:3], v[168:171], v[220:223], v[0:3]
	v_mfma_f32_16x16x32_bf16 v[54:57], v[150:153], v[186:189], v[54:57]
	v_mfma_f32_16x16x32_bf16 v[50:53], v[172:175], v[186:189], v[50:53]
	v_mfma_f32_16x16x32_bf16 v[36:39], v[150:153], v[194:197], v[36:39]
	v_mfma_f32_16x16x32_bf16 v[32:35], v[172:175], v[194:197], v[32:35]
	v_mfma_f32_16x16x32_bf16 v[20:23], v[150:153], v[216:219], v[20:23]
	v_mfma_f32_16x16x32_bf16 v[16:19], v[172:175], v[216:219], v[16:19]
	v_mfma_f32_16x16x32_bf16 v[4:7], v[150:153], v[224:227], v[4:7]
	v_mfma_f32_16x16x32_bf16 v[0:3], v[172:175], v[224:227], v[0:3]
	s_setprio 0
	s_barrier
	s_add_i32 s6, 0, 0x18000
	v_add_u32_e32 v48, s6, v183
	s_add_i32 s26, 0, 0x1c000
	ds_read_b128 v[122:125], v48
	ds_read_b128 v[130:133], v48 offset:1024
	ds_read_b128 v[138:141], v48 offset:2048
	ds_read_b128 v[142:145], v48 offset:3072
	v_add_u32_e32 v48, s26, v183
	ds_read_b128 v[146:149], v48
	ds_read_b128 v[150:153], v48 offset:1024
	ds_read_b128 v[168:171], v48 offset:2048
	ds_read_b128 v[172:175], v48 offset:3072
	s_add_u32 s20, s60, 0x40000
	s_addc_u32 s21, s61, 0
	s_mov_b32 m0, s63
	v_lshl_add_u64 v[228:229], s[20:21], 0, v[156:157]
	ds_read_b128 v[176:179], v185 offset:32768
	ds_read_b128 v[186:189], v185 offset:33792
	ds_read_b128 v[190:193], v185 offset:34816
	ds_read_b128 v[194:197], v185 offset:35840
	ds_read_b128 v[198:201], v185 offset:36864
	ds_read_b128 v[216:219], v185 offset:37888
	ds_read_b128 v[220:223], v185 offset:38912
	ds_read_b128 v[224:227], v185 offset:39936
	global_load_lds_dwordx4 v[228:229], off
	v_lshl_add_u64 v[228:229], s[20:21], 0, v[160:161]
	s_mov_b32 m0, s64
	s_nop 0
	global_load_lds_dwordx4 v[228:229], off
	s_waitcnt vmcnt(8)
	s_waitcnt lgkmcnt(0)
	s_barrier
	s_setprio 1
	v_mfma_f32_16x16x32_bf16 v[134:137], v[122:125], v[176:179], v[134:137]
	v_mfma_f32_16x16x32_bf16 v[126:129], v[138:141], v[176:179], v[126:129]
	v_mfma_f32_16x16x32_bf16 v[110:113], v[122:125], v[190:193], v[110:113]
	v_mfma_f32_16x16x32_bf16 v[106:109], v[138:141], v[190:193], v[106:109]
	v_mfma_f32_16x16x32_bf16 v[94:97], v[122:125], v[198:201], v[94:97]
	v_mfma_f32_16x16x32_bf16 v[90:93], v[138:141], v[198:201], v[90:93]
	v_mfma_f32_16x16x32_bf16 v[78:81], v[122:125], v[220:223], v[78:81]
	v_mfma_f32_16x16x32_bf16 v[74:77], v[138:141], v[220:223], v[74:77]
	v_mfma_f32_16x16x32_bf16 v[134:137], v[130:133], v[186:189], v[134:137]
	v_mfma_f32_16x16x32_bf16 v[126:129], v[142:145], v[186:189], v[126:129]
	v_mfma_f32_16x16x32_bf16 v[110:113], v[130:133], v[194:197], v[110:113]
	v_mfma_f32_16x16x32_bf16 v[106:109], v[142:145], v[194:197], v[106:109]
	v_mfma_f32_16x16x32_bf16 v[94:97], v[130:133], v[216:219], v[94:97]
	v_mfma_f32_16x16x32_bf16 v[90:93], v[142:145], v[216:219], v[90:93]
	v_mfma_f32_16x16x32_bf16 v[78:81], v[130:133], v[224:227], v[78:81]
	v_mfma_f32_16x16x32_bf16 v[74:77], v[142:145], v[224:227], v[74:77]
	v_mfma_f32_16x16x32_bf16 v[118:121], v[146:149], v[176:179], v[118:121]
	v_mfma_f32_16x16x32_bf16 v[114:117], v[168:171], v[176:179], v[114:117]
	v_mfma_f32_16x16x32_bf16 v[102:105], v[146:149], v[190:193], v[102:105]
	v_mfma_f32_16x16x32_bf16 v[98:101], v[168:171], v[190:193], v[98:101]
	v_mfma_f32_16x16x32_bf16 v[86:89], v[146:149], v[198:201], v[86:89]
	v_mfma_f32_16x16x32_bf16 v[82:85], v[168:171], v[198:201], v[82:85]
	v_mfma_f32_16x16x32_bf16 v[70:73], v[146:149], v[220:223], v[70:73]
	v_mfma_f32_16x16x32_bf16 v[66:69], v[168:171], v[220:223], v[66:69]
	v_mfma_f32_16x16x32_bf16 v[118:121], v[150:153], v[186:189], v[118:121]
	v_mfma_f32_16x16x32_bf16 v[114:117], v[172:175], v[186:189], v[114:117]
	v_mfma_f32_16x16x32_bf16 v[102:105], v[150:153], v[194:197], v[102:105]
	v_mfma_f32_16x16x32_bf16 v[98:101], v[172:175], v[194:197], v[98:101]
	v_mfma_f32_16x16x32_bf16 v[86:89], v[150:153], v[216:219], v[86:89]
	v_mfma_f32_16x16x32_bf16 v[82:85], v[172:175], v[216:219], v[82:85]
	v_mfma_f32_16x16x32_bf16 v[70:73], v[150:153], v[224:227], v[70:73]
	v_mfma_f32_16x16x32_bf16 v[66:69], v[172:175], v[224:227], v[66:69]
	s_setprio 0
	s_barrier
	s_add_i32 s6, s6, s24
	v_lshl_add_u64 v[180:181], v[180:181], 0, s[30:31]
	s_mov_b32 m0, s6
	ds_read_b128 v[176:179], v185 offset:49152
	ds_read_b128 v[186:189], v185 offset:50176
	ds_read_b128 v[190:193], v185 offset:51200
	ds_read_b128 v[194:197], v185 offset:52224
	ds_read_b128 v[198:201], v185 offset:53248
	ds_read_b128 v[216:219], v185 offset:54272
	ds_read_b128 v[220:223], v185 offset:55296
	ds_read_b128 v[224:227], v185 offset:56320
	global_load_lds_dwordx4 v[180:181], off
	s_add_i32 m0, s6, 0x2000
	s_add_u32 s20, s58, 0x40080
	v_lshl_add_u64 v[180:181], v[202:203], 0, s[30:31]
	s_addc_u32 s21, s59, 0
	s_add_i32 s6, s26, s24
	global_load_lds_dwordx4 v[180:181], off
	v_lshl_add_u64 v[180:181], s[20:21], 0, v[158:159]
	s_mov_b32 m0, s6
	s_nop 0
	global_load_lds_dwordx4 v[180:181], off
	v_lshl_add_u64 v[180:181], s[20:21], 0, v[162:163]
	s_add_i32 m0, s6, 0x2000
	s_nop 0
	global_load_lds_dwordx4 v[180:181], off
	v_lshl_add_u64 v[180:181], v[212:213], 0, s[30:31]
	s_mov_b32 m0, s65
	s_nop 0
	global_load_lds_dwordx4 v[180:181], off
	v_lshl_add_u64 v[180:181], v[214:215], 0, s[30:31]
	s_mov_b32 m0, s66
	s_nop 0
	global_load_lds_dwordx4 v[180:181], off
	s_waitcnt vmcnt(8)
	s_waitcnt lgkmcnt(0)
	s_barrier
	s_setprio 1
	v_mfma_f32_16x16x32_bf16 v[62:65], v[122:125], v[176:179], v[62:65]
	v_mfma_f32_16x16x32_bf16 v[58:61], v[138:141], v[176:179], v[58:61]
	v_mfma_f32_16x16x32_bf16 v[44:47], v[122:125], v[190:193], v[44:47]
	v_mfma_f32_16x16x32_bf16 v[40:43], v[138:141], v[190:193], v[40:43]
	v_mfma_f32_16x16x32_bf16 v[28:31], v[122:125], v[198:201], v[28:31]
	v_mfma_f32_16x16x32_bf16 v[24:27], v[138:141], v[198:201], v[24:27]
	v_mfma_f32_16x16x32_bf16 v[12:15], v[122:125], v[220:223], v[12:15]
	v_mfma_f32_16x16x32_bf16 v[8:11], v[138:141], v[220:223], v[8:11]
	v_mfma_f32_16x16x32_bf16 v[62:65], v[130:133], v[186:189], v[62:65]
	v_mfma_f32_16x16x32_bf16 v[58:61], v[142:145], v[186:189], v[58:61]
	v_mfma_f32_16x16x32_bf16 v[44:47], v[130:133], v[194:197], v[44:47]
	v_mfma_f32_16x16x32_bf16 v[40:43], v[142:145], v[194:197], v[40:43]
	v_mfma_f32_16x16x32_bf16 v[28:31], v[130:133], v[216:219], v[28:31]
	v_mfma_f32_16x16x32_bf16 v[24:27], v[142:145], v[216:219], v[24:27]
	v_mfma_f32_16x16x32_bf16 v[12:15], v[130:133], v[224:227], v[12:15]
	v_mfma_f32_16x16x32_bf16 v[8:11], v[142:145], v[224:227], v[8:11]
	v_mfma_f32_16x16x32_bf16 v[54:57], v[146:149], v[176:179], v[54:57]
	v_mfma_f32_16x16x32_bf16 v[50:53], v[168:171], v[176:179], v[50:53]
	v_mfma_f32_16x16x32_bf16 v[36:39], v[146:149], v[190:193], v[36:39]
	v_mfma_f32_16x16x32_bf16 v[32:35], v[168:171], v[190:193], v[32:35]
	v_mfma_f32_16x16x32_bf16 v[20:23], v[146:149], v[198:201], v[20:23]
	v_mfma_f32_16x16x32_bf16 v[16:19], v[168:171], v[198:201], v[16:19]
	v_mfma_f32_16x16x32_bf16 v[4:7], v[146:149], v[220:223], v[4:7]
	v_mfma_f32_16x16x32_bf16 v[0:3], v[168:171], v[220:223], v[0:3]
	v_mfma_f32_16x16x32_bf16 v[54:57], v[150:153], v[186:189], v[54:57]
	v_mfma_f32_16x16x32_bf16 v[50:53], v[172:175], v[186:189], v[50:53]
	v_mfma_f32_16x16x32_bf16 v[36:39], v[150:153], v[194:197], v[36:39]
	v_mfma_f32_16x16x32_bf16 v[32:35], v[172:175], v[194:197], v[32:35]
	v_mfma_f32_16x16x32_bf16 v[20:23], v[150:153], v[216:219], v[20:23]
	v_mfma_f32_16x16x32_bf16 v[16:19], v[172:175], v[216:219], v[16:19]
	v_mfma_f32_16x16x32_bf16 v[4:7], v[150:153], v[224:227], v[4:7]
	v_mfma_f32_16x16x32_bf16 v[0:3], v[172:175], v[224:227], v[0:3]
	s_setprio 0
	s_add_i32 s70, s70, 2
	s_add_u32 s56, s56, 0x100
	s_addc_u32 s57, s57, 0
	s_add_u32 s53, s53, 0x100
	s_addc_u32 s69, s69, 0
	s_add_u32 s6, s56, 0xfffc0080
	s_addc_u32 s20, s57, -1
	s_cmp_eq_u32 s70, 12
	s_cselect_b32 s61, s18, s20
	s_cselect_b32 s60, s33, s6
	s_cselect_b32 s59, s45, s69
	s_cselect_b32 s58, s47, s53
	s_cmp_gt_u32 s70, 13
	s_barrier
	s_cbranch_scc0 .LBB0_1301
	s_and_b64 vcc, exec, s[40:41]
	s_cbranch_vccz .LBB0_1304
	s_barrier

.LBB0_1410:
	s_ashr_i32 s43, s42, 31
	s_lshl_b64 s[20:21], s[42:43], 19
	s_add_u32 s48, s16, s20
	s_addc_u32 s49, s17, s21
	s_and_b64 s[20:21], s[46:47], exec
	s_cselect_b32 s33, s49, s53
	s_cselect_b32 s39, s48, s52
	s_ashr_i32 s45, s44, 31
	s_lshl_b64 s[20:21], s[44:45], 19
	s_add_u32 s50, s8, s20
	s_addc_u32 s51, s9, s21
	s_and_b64 s[20:21], s[46:47], exec
	s_cselect_b32 s43, s51, s55
	s_cselect_b32 s45, s50, s54
	s_add_u32 s52, s52, 0x40080
	s_addc_u32 s53, s53, 0
	s_add_u32 s65, s54, 0x100
	v_mov_b32_e32 v0, 0
	s_addc_u32 s66, s55, 0
	s_mov_b32 s67, -2
	v_mov_b32_e32 v1, v0
	v_mov_b32_e32 v2, v0
	v_mov_b32_e32 v3, v0
	v_mov_b32_e32 v4, v0
	v_mov_b32_e32 v5, v0
	v_mov_b32_e32 v6, v0
	v_mov_b32_e32 v7, v0
	v_mov_b32_e32 v16, v0
	v_mov_b32_e32 v17, v0
	v_mov_b32_e32 v18, v0
	v_mov_b32_e32 v19, v0
	v_mov_b32_e32 v20, v0
	v_mov_b32_e32 v21, v0
	v_mov_b32_e32 v22, v0
	v_mov_b32_e32 v23, v0
	v_mov_b32_e32 v32, v0
	v_mov_b32_e32 v33, v0
	v_mov_b32_e32 v34, v0
	v_mov_b32_e32 v35, v0
	v_mov_b32_e32 v36, v0
	v_mov_b32_e32 v37, v0
	v_mov_b32_e32 v38, v0
	v_mov_b32_e32 v39, v0
	v_mov_b32_e32 v50, v0
	v_mov_b32_e32 v51, v0
	v_mov_b32_e32 v52, v0
	v_mov_b32_e32 v53, v0
	v_mov_b32_e32 v54, v0
	v_mov_b32_e32 v55, v0
	v_mov_b32_e32 v56, v0
	v_mov_b32_e32 v57, v0
	v_mov_b32_e32 v8, v0
	v_mov_b32_e32 v9, v0
	v_mov_b32_e32 v10, v0
	v_mov_b32_e32 v11, v0
	v_mov_b32_e32 v12, v0
	v_mov_b32_e32 v13, v0
	v_mov_b32_e32 v14, v0
	v_mov_b32_e32 v15, v0
	v_mov_b32_e32 v24, v0
	v_mov_b32_e32 v25, v0
	v_mov_b32_e32 v26, v0
	v_mov_b32_e32 v27, v0
	v_mov_b32_e32 v28, v0
	v_mov_b32_e32 v29, v0
	v_mov_b32_e32 v30, v0
	v_mov_b32_e32 v31, v0
	v_mov_b32_e32 v40, v0
	v_mov_b32_e32 v41, v0
	v_mov_b32_e32 v42, v0
	v_mov_b32_e32 v43, v0
	v_mov_b32_e32 v44, v0
	v_mov_b32_e32 v45, v0
	v_mov_b32_e32 v46, v0
	v_mov_b32_e32 v47, v0
	v_mov_b32_e32 v58, v0
	v_mov_b32_e32 v59, v0
	v_mov_b32_e32 v60, v0
	v_mov_b32_e32 v61, v0
	v_mov_b32_e32 v62, v0
	v_mov_b32_e32 v63, v0
	v_mov_b32_e32 v64, v0
	v_mov_b32_e32 v65, v0
	v_mov_b32_e32 v66, v0
	v_mov_b32_e32 v67, v0
	v_mov_b32_e32 v68, v0
	v_mov_b32_e32 v69, v0
	v_mov_b32_e32 v70, v0
	v_mov_b32_e32 v71, v0
	v_mov_b32_e32 v72, v0
	v_mov_b32_e32 v73, v0
	v_mov_b32_e32 v82, v0
	v_mov_b32_e32 v83, v0
	v_mov_b32_e32 v84, v0
	v_mov_b32_e32 v85, v0
	v_mov_b32_e32 v86, v0
	v_mov_b32_e32 v87, v0
	v_mov_b32_e32 v88, v0
	v_mov_b32_e32 v89, v0
	v_mov_b32_e32 v98, v0
	v_mov_b32_e32 v99, v0
	v_mov_b32_e32 v100, v0
	v_mov_b32_e32 v101, v0
	v_mov_b32_e32 v102, v0
	v_mov_b32_e32 v103, v0
	v_mov_b32_e32 v104, v0
	v_mov_b32_e32 v105, v0
	v_mov_b32_e32 v114, v0
	v_mov_b32_e32 v115, v0
	v_mov_b32_e32 v116, v0
	v_mov_b32_e32 v117, v0
	v_mov_b32_e32 v118, v0
	v_mov_b32_e32 v119, v0
	v_mov_b32_e32 v120, v0
	v_mov_b32_e32 v121, v0
	v_mov_b32_e32 v74, v0
	v_mov_b32_e32 v75, v0
	v_mov_b32_e32 v76, v0
	v_mov_b32_e32 v77, v0
	v_mov_b32_e32 v78, v0
	v_mov_b32_e32 v79, v0
	v_mov_b32_e32 v80, v0
	v_mov_b32_e32 v81, v0
	v_mov_b32_e32 v90, v0
	v_mov_b32_e32 v91, v0
	v_mov_b32_e32 v92, v0
	v_mov_b32_e32 v93, v0
	v_mov_b32_e32 v94, v0
	v_mov_b32_e32 v95, v0
	v_mov_b32_e32 v96, v0
	v_mov_b32_e32 v97, v0
	v_mov_b32_e32 v106, v0
	v_mov_b32_e32 v107, v0
	v_mov_b32_e32 v108, v0
	v_mov_b32_e32 v109, v0
	v_mov_b32_e32 v110, v0
	v_mov_b32_e32 v111, v0
	v_mov_b32_e32 v112, v0
	v_mov_b32_e32 v113, v0
	v_mov_b32_e32 v122, v0
	v_mov_b32_e32 v123, v0
	v_mov_b32_e32 v124, v0
	v_mov_b32_e32 v125, v0
	v_mov_b32_e32 v126, v0
	v_mov_b32_e32 v127, v0
	v_mov_b32_e32 v128, v0
	v_mov_b32_e32 v129, v0
	s_add_u32 s6, s52, 0xfffc0080
	s_addc_u32 s20, s53, -1
	s_cmp_eq_u32 s67, 12
	s_cselect_b32 s57, s33, s20
	s_cselect_b32 s56, s39, s6
	s_cselect_b32 s55, s43, s66
	s_cselect_b32 s54, s45, s65
.LBB0_1411:
	s_add_i32 s21, 0, 0x10000
	v_add_u32_e32 v48, s21, v173
	s_add_i32 s6, 0, 0x14000
	ds_read_b128 v[138:141], v48
	ds_read_b128 v[142:145], v48 offset:1024
	ds_read_b128 v[146:149], v48 offset:2048
	ds_read_b128 v[150:153], v48 offset:3072
	v_add_u32_e32 v48, s6, v173
	ds_read_b128 v[156:159], v48
	ds_read_b128 v[160:163], v48 offset:1024
	ds_read_b128 v[164:167], v48 offset:2048
	ds_read_b128 v[168:171], v48 offset:3072
	v_lshl_add_u64 v[202:203], s[52:53], 0, v[134:135]
	s_add_i32 m0, s59, 0xc000
	ds_read_b128 v[178:181], v176
	ds_read_b128 v[182:185], v176 offset:1024
	ds_read_b128 v[186:189], v176 offset:2048
	ds_read_b128 v[190:193], v176 offset:3072
	ds_read_b128 v[194:197], v176 offset:4096
	ds_read_b128 v[198:201], v176 offset:5120
	ds_read_b128 v[216:219], v176 offset:6144
	ds_read_b128 v[220:223], v176 offset:7168
	global_load_lds_dwordx4 v[202:203], off
	v_lshl_add_u64 v[202:203], s[52:53], 0, v[136:137]
	s_add_i32 m0, s59, 0xe000
	s_nop 0
	global_load_lds_dwordx4 v[202:203], off
	s_waitcnt vmcnt(8)
	s_waitcnt lgkmcnt(0)
	s_barrier
	s_setprio 1
	v_mfma_f32_16x16x32_bf16 v[126:129], v[138:141], v[178:181], v[126:129]
	v_mfma_f32_16x16x32_bf16 v[122:125], v[146:149], v[178:181], v[122:125]
	v_mfma_f32_16x16x32_bf16 v[110:113], v[138:141], v[186:189], v[110:113]
	v_mfma_f32_16x16x32_bf16 v[106:109], v[146:149], v[186:189], v[106:109]
	v_mfma_f32_16x16x32_bf16 v[94:97], v[138:141], v[194:197], v[94:97]
	v_mfma_f32_16x16x32_bf16 v[90:93], v[146:149], v[194:197], v[90:93]
	v_mfma_f32_16x16x32_bf16 v[78:81], v[138:141], v[216:219], v[78:81]
	v_mfma_f32_16x16x32_bf16 v[74:77], v[146:149], v[216:219], v[74:77]
	v_mfma_f32_16x16x32_bf16 v[126:129], v[142:145], v[182:185], v[126:129]
	v_mfma_f32_16x16x32_bf16 v[122:125], v[150:153], v[182:185], v[122:125]
	v_mfma_f32_16x16x32_bf16 v[110:113], v[142:145], v[190:193], v[110:113]
	v_mfma_f32_16x16x32_bf16 v[106:109], v[150:153], v[190:193], v[106:109]
	v_mfma_f32_16x16x32_bf16 v[94:97], v[142:145], v[198:201], v[94:97]
	v_mfma_f32_16x16x32_bf16 v[90:93], v[150:153], v[198:201], v[90:93]
	v_mfma_f32_16x16x32_bf16 v[78:81], v[142:145], v[220:223], v[78:81]
	v_mfma_f32_16x16x32_bf16 v[74:77], v[150:153], v[220:223], v[74:77]
	v_mfma_f32_16x16x32_bf16 v[118:121], v[156:159], v[178:181], v[118:121]
	v_mfma_f32_16x16x32_bf16 v[114:117], v[164:167], v[178:181], v[114:117]
	v_mfma_f32_16x16x32_bf16 v[102:105], v[156:159], v[186:189], v[102:105]
	v_mfma_f32_16x16x32_bf16 v[98:101], v[164:167], v[186:189], v[98:101]
	v_mfma_f32_16x16x32_bf16 v[86:89], v[156:159], v[194:197], v[86:89]
	v_mfma_f32_16x16x32_bf16 v[82:85], v[164:167], v[194:197], v[82:85]
	v_mfma_f32_16x16x32_bf16 v[70:73], v[156:159], v[216:219], v[70:73]
	v_mfma_f32_16x16x32_bf16 v[66:69], v[164:167], v[216:219], v[66:69]
	v_mfma_f32_16x16x32_bf16 v[118:121], v[160:163], v[182:185], v[118:121]
	v_mfma_f32_16x16x32_bf16 v[114:117], v[168:171], v[182:185], v[114:117]
	v_mfma_f32_16x16x32_bf16 v[102:105], v[160:163], v[190:193], v[102:105]
	v_mfma_f32_16x16x32_bf16 v[98:101], v[168:171], v[190:193], v[98:101]
	v_mfma_f32_16x16x32_bf16 v[86:89], v[160:163], v[198:201], v[86:89]
	v_mfma_f32_16x16x32_bf16 v[82:85], v[168:171], v[198:201], v[82:85]
	v_mfma_f32_16x16x32_bf16 v[70:73], v[160:163], v[220:223], v[70:73]
	v_mfma_f32_16x16x32_bf16 v[66:69], v[168:171], v[220:223], v[66:69]
	s_setprio 0
	s_barrier
	s_add_i32 s20, s21, s58
	v_lshl_add_u64 v[202:203], s[54:55], 0, v[132:133]
	s_mov_b32 m0, s20
	ds_read_b128 v[178:181], v176 offset:16384
	ds_read_b128 v[182:185], v176 offset:17408
	ds_read_b128 v[186:189], v176 offset:18432
	ds_read_b128 v[190:193], v176 offset:19456
	ds_read_b128 v[194:197], v176 offset:20480
	ds_read_b128 v[198:201], v176 offset:21504
	ds_read_b128 v[216:219], v176 offset:22528
	ds_read_b128 v[220:223], v176 offset:23552
	global_load_lds_dwordx4 v[202:203], off
	s_add_i32 m0, s20, 0x2000
	s_add_u32 s20, s54, 0x40000
	v_lshl_add_u64 v[212:213], s[54:55], 0, v[130:131]
	s_addc_u32 s21, s55, 0
	s_add_i32 s6, s6, s58
	global_load_lds_dwordx4 v[212:213], off
	v_lshl_add_u64 v[214:215], s[20:21], 0, v[132:133]
	s_mov_b32 m0, s6
	v_lshl_add_u64 v[224:225], s[56:57], 0, v[130:131]
	global_load_lds_dwordx4 v[214:215], off
	v_lshl_add_u64 v[214:215], s[20:21], 0, v[130:131]
	s_add_i32 m0, s6, 0x2000
	s_nop 0
	global_load_lds_dwordx4 v[214:215], off
	v_lshl_add_u64 v[214:215], s[56:57], 0, v[132:133]
	s_mov_b32 m0, s59
	s_nop 0
	global_load_lds_dwordx4 v[214:215], off
	s_mov_b32 m0, s60
	s_nop 0
	global_load_lds_dwordx4 v[224:225], off
	s_waitcnt vmcnt(8)
	s_waitcnt lgkmcnt(0)
	s_barrier
	s_setprio 1
	v_mfma_f32_16x16x32_bf16 v[62:65], v[138:141], v[178:181], v[62:65]
	v_mfma_f32_16x16x32_bf16 v[58:61], v[146:149], v[178:181], v[58:61]
	v_mfma_f32_16x16x32_bf16 v[44:47], v[138:141], v[186:189], v[44:47]
	v_mfma_f32_16x16x32_bf16 v[40:43], v[146:149], v[186:189], v[40:43]
	v_mfma_f32_16x16x32_bf16 v[28:31], v[138:141], v[194:197], v[28:31]
	v_mfma_f32_16x16x32_bf16 v[24:27], v[146:149], v[194:197], v[24:27]
	v_mfma_f32_16x16x32_bf16 v[12:15], v[138:141], v[216:219], v[12:15]
	v_mfma_f32_16x16x32_bf16 v[8:11], v[146:149], v[216:219], v[8:11]
	v_mfma_f32_16x16x32_bf16 v[62:65], v[142:145], v[182:185], v[62:65]
	v_mfma_f32_16x16x32_bf16 v[58:61], v[150:153], v[182:185], v[58:61]
	v_mfma_f32_16x16x32_bf16 v[44:47], v[142:145], v[190:193], v[44:47]
	v_mfma_f32_16x16x32_bf16 v[40:43], v[150:153], v[190:193], v[40:43]
	v_mfma_f32_16x16x32_bf16 v[28:31], v[142:145], v[198:201], v[28:31]
	v_mfma_f32_16x16x32_bf16 v[24:27], v[150:153], v[198:201], v[24:27]
	v_mfma_f32_16x16x32_bf16 v[12:15], v[142:145], v[220:223], v[12:15]
	v_mfma_f32_16x16x32_bf16 v[8:11], v[150:153], v[220:223], v[8:11]
	v_mfma_f32_16x16x32_bf16 v[54:57], v[156:159], v[178:181], v[54:57]
	v_mfma_f32_16x16x32_bf16 v[50:53], v[164:167], v[178:181], v[50:53]
	v_mfma_f32_16x16x32_bf16 v[36:39], v[156:159], v[186:189], v[36:39]
	v_mfma_f32_16x16x32_bf16 v[32:35], v[164:167], v[186:189], v[32:35]
	v_mfma_f32_16x16x32_bf16 v[20:23], v[156:159], v[194:197], v[20:23]
	v_mfma_f32_16x16x32_bf16 v[16:19], v[164:167], v[194:197], v[16:19]
	v_mfma_f32_16x16x32_bf16 v[4:7], v[156:159], v[216:219], v[4:7]
	v_mfma_f32_16x16x32_bf16 v[0:3], v[164:167], v[216:219], v[0:3]
	v_mfma_f32_16x16x32_bf16 v[54:57], v[160:163], v[182:185], v[54:57]
	v_mfma_f32_16x16x32_bf16 v[50:53], v[168:171], v[182:185], v[50:53]
	v_mfma_f32_16x16x32_bf16 v[36:39], v[160:163], v[190:193], v[36:39]
	v_mfma_f32_16x16x32_bf16 v[32:35], v[168:171], v[190:193], v[32:35]
	v_mfma_f32_16x16x32_bf16 v[20:23], v[160:163], v[198:201], v[20:23]
	v_mfma_f32_16x16x32_bf16 v[16:19], v[168:171], v[198:201], v[16:19]
	v_mfma_f32_16x16x32_bf16 v[4:7], v[160:163], v[220:223], v[4:7]
	v_mfma_f32_16x16x32_bf16 v[0:3], v[168:171], v[220:223], v[0:3]
	s_setprio 0
	s_barrier
	s_add_i32 s6, 0, 0x18000
	v_add_u32_e32 v48, s6, v173
	s_add_i32 s26, 0, 0x1c000
	ds_read_b128 v[138:141], v48
	ds_read_b128 v[142:145], v48 offset:1024
	ds_read_b128 v[146:149], v48 offset:2048
	ds_read_b128 v[150:153], v48 offset:3072
	v_add_u32_e32 v48, s26, v173
	ds_read_b128 v[156:159], v48
	ds_read_b128 v[160:163], v48 offset:1024
	ds_read_b128 v[164:167], v48 offset:2048
	ds_read_b128 v[168:171], v48 offset:3072
	s_add_u32 s20, s56, 0x40000
	s_addc_u32 s21, s57, 0
	s_mov_b32 m0, s61
	v_lshl_add_u64 v[226:227], s[20:21], 0, v[132:133]
	ds_read_b128 v[178:181], v176 offset:32768
	ds_read_b128 v[182:185], v176 offset:33792
	ds_read_b128 v[186:189], v176 offset:34816
	ds_read_b128 v[190:193], v176 offset:35840
	ds_read_b128 v[194:197], v176 offset:36864
	ds_read_b128 v[198:201], v176 offset:37888
	ds_read_b128 v[216:219], v176 offset:38912
	ds_read_b128 v[220:223], v176 offset:39936
	global_load_lds_dwordx4 v[226:227], off
	v_lshl_add_u64 v[226:227], s[20:21], 0, v[130:131]
	s_mov_b32 m0, s62
	s_nop 0
	global_load_lds_dwordx4 v[226:227], off
	s_waitcnt vmcnt(8)
	s_waitcnt lgkmcnt(0)
	s_barrier
	s_setprio 1
	v_mfma_f32_16x16x32_bf16 v[126:129], v[138:141], v[178:181], v[126:129]
	v_mfma_f32_16x16x32_bf16 v[122:125], v[146:149], v[178:181], v[122:125]
	v_mfma_f32_16x16x32_bf16 v[110:113], v[138:141], v[186:189], v[110:113]
	v_mfma_f32_16x16x32_bf16 v[106:109], v[146:149], v[186:189], v[106:109]
	v_mfma_f32_16x16x32_bf16 v[94:97], v[138:141], v[194:197], v[94:97]
	v_mfma_f32_16x16x32_bf16 v[90:93], v[146:149], v[194:197], v[90:93]
	v_mfma_f32_16x16x32_bf16 v[78:81], v[138:141], v[216:219], v[78:81]
	v_mfma_f32_16x16x32_bf16 v[74:77], v[146:149], v[216:219], v[74:77]
	v_mfma_f32_16x16x32_bf16 v[126:129], v[142:145], v[182:185], v[126:129]
	v_mfma_f32_16x16x32_bf16 v[122:125], v[150:153], v[182:185], v[122:125]
	v_mfma_f32_16x16x32_bf16 v[110:113], v[142:145], v[190:193], v[110:113]
	v_mfma_f32_16x16x32_bf16 v[106:109], v[150:153], v[190:193], v[106:109]
	v_mfma_f32_16x16x32_bf16 v[94:97], v[142:145], v[198:201], v[94:97]
	v_mfma_f32_16x16x32_bf16 v[90:93], v[150:153], v[198:201], v[90:93]
	v_mfma_f32_16x16x32_bf16 v[78:81], v[142:145], v[220:223], v[78:81]
	v_mfma_f32_16x16x32_bf16 v[74:77], v[150:153], v[220:223], v[74:77]
	v_mfma_f32_16x16x32_bf16 v[118:121], v[156:159], v[178:181], v[118:121]
	v_mfma_f32_16x16x32_bf16 v[114:117], v[164:167], v[178:181], v[114:117]
	v_mfma_f32_16x16x32_bf16 v[102:105], v[156:159], v[186:189], v[102:105]
	v_mfma_f32_16x16x32_bf16 v[98:101], v[164:167], v[186:189], v[98:101]
	v_mfma_f32_16x16x32_bf16 v[86:89], v[156:159], v[194:197], v[86:89]
	v_mfma_f32_16x16x32_bf16 v[82:85], v[164:167], v[194:197], v[82:85]
	v_mfma_f32_16x16x32_bf16 v[70:73], v[156:159], v[216:219], v[70:73]
	v_mfma_f32_16x16x32_bf16 v[66:69], v[164:167], v[216:219], v[66:69]
	v_mfma_f32_16x16x32_bf16 v[118:121], v[160:163], v[182:185], v[118:121]
	v_mfma_f32_16x16x32_bf16 v[114:117], v[168:171], v[182:185], v[114:117]
	v_mfma_f32_16x16x32_bf16 v[102:105], v[160:163], v[190:193], v[102:105]
	v_mfma_f32_16x16x32_bf16 v[98:101], v[168:171], v[190:193], v[98:101]
	v_mfma_f32_16x16x32_bf16 v[86:89], v[160:163], v[198:201], v[86:89]
	v_mfma_f32_16x16x32_bf16 v[82:85], v[168:171], v[198:201], v[82:85]
	v_mfma_f32_16x16x32_bf16 v[70:73], v[160:163], v[220:223], v[70:73]
	v_mfma_f32_16x16x32_bf16 v[66:69], v[168:171], v[220:223], v[66:69]
	s_setprio 0
	s_barrier
	s_add_i32 s6, s6, s58
	v_lshl_add_u64 v[202:203], v[202:203], 0, s[30:31]
	s_mov_b32 m0, s6
	ds_read_b128 v[178:181], v176 offset:49152
	ds_read_b128 v[182:185], v176 offset:50176
	ds_read_b128 v[186:189], v176 offset:51200
	ds_read_b128 v[190:193], v176 offset:52224
	ds_read_b128 v[194:197], v176 offset:53248
	ds_read_b128 v[198:201], v176 offset:54272
	ds_read_b128 v[216:219], v176 offset:55296
	ds_read_b128 v[220:223], v176 offset:56320
	global_load_lds_dwordx4 v[202:203], off
	s_add_i32 m0, s6, 0x2000
	s_add_u32 s20, s54, 0x40080
	v_lshl_add_u64 v[202:203], v[212:213], 0, s[30:31]
	s_addc_u32 s21, s55, 0
	s_add_i32 s6, s26, s58
	global_load_lds_dwordx4 v[202:203], off
	v_lshl_add_u64 v[202:203], s[20:21], 0, v[132:133]
	s_mov_b32 m0, s6
	s_nop 0
	global_load_lds_dwordx4 v[202:203], off
	v_lshl_add_u64 v[202:203], s[20:21], 0, v[130:131]
	s_add_i32 m0, s6, 0x2000
	s_nop 0
	global_load_lds_dwordx4 v[202:203], off
	v_lshl_add_u64 v[202:203], v[214:215], 0, s[30:31]
	s_mov_b32 m0, s24
	s_nop 0
	global_load_lds_dwordx4 v[202:203], off
	v_lshl_add_u64 v[202:203], v[224:225], 0, s[30:31]
	s_mov_b32 m0, s63
	s_nop 0
	global_load_lds_dwordx4 v[202:203], off
	s_waitcnt vmcnt(8)
	s_waitcnt lgkmcnt(0)
	s_barrier
	s_setprio 1
	v_mfma_f32_16x16x32_bf16 v[62:65], v[138:141], v[178:181], v[62:65]
	v_mfma_f32_16x16x32_bf16 v[58:61], v[146:149], v[178:181], v[58:61]
	v_mfma_f32_16x16x32_bf16 v[44:47], v[138:141], v[186:189], v[44:47]
	v_mfma_f32_16x16x32_bf16 v[40:43], v[146:149], v[186:189], v[40:43]
	v_mfma_f32_16x16x32_bf16 v[28:31], v[138:141], v[194:197], v[28:31]
	v_mfma_f32_16x16x32_bf16 v[24:27], v[146:149], v[194:197], v[24:27]
	v_mfma_f32_16x16x32_bf16 v[12:15], v[138:141], v[216:219], v[12:15]
	v_mfma_f32_16x16x32_bf16 v[8:11], v[146:149], v[216:219], v[8:11]
	v_mfma_f32_16x16x32_bf16 v[62:65], v[142:145], v[182:185], v[62:65]
	v_mfma_f32_16x16x32_bf16 v[58:61], v[150:153], v[182:185], v[58:61]
	v_mfma_f32_16x16x32_bf16 v[44:47], v[142:145], v[190:193], v[44:47]
	v_mfma_f32_16x16x32_bf16 v[40:43], v[150:153], v[190:193], v[40:43]
	v_mfma_f32_16x16x32_bf16 v[28:31], v[142:145], v[198:201], v[28:31]
	v_mfma_f32_16x16x32_bf16 v[24:27], v[150:153], v[198:201], v[24:27]
	v_mfma_f32_16x16x32_bf16 v[12:15], v[142:145], v[220:223], v[12:15]
	v_mfma_f32_16x16x32_bf16 v[8:11], v[150:153], v[220:223], v[8:11]
	v_mfma_f32_16x16x32_bf16 v[54:57], v[156:159], v[178:181], v[54:57]
	v_mfma_f32_16x16x32_bf16 v[50:53], v[164:167], v[178:181], v[50:53]
	v_mfma_f32_16x16x32_bf16 v[36:39], v[156:159], v[186:189], v[36:39]
	v_mfma_f32_16x16x32_bf16 v[32:35], v[164:167], v[186:189], v[32:35]
	v_mfma_f32_16x16x32_bf16 v[20:23], v[156:159], v[194:197], v[20:23]
	v_mfma_f32_16x16x32_bf16 v[16:19], v[164:167], v[194:197], v[16:19]
	v_mfma_f32_16x16x32_bf16 v[4:7], v[156:159], v[216:219], v[4:7]
	v_mfma_f32_16x16x32_bf16 v[0:3], v[164:167], v[216:219], v[0:3]
	v_mfma_f32_16x16x32_bf16 v[54:57], v[160:163], v[182:185], v[54:57]
	v_mfma_f32_16x16x32_bf16 v[50:53], v[168:171], v[182:185], v[50:53]
	v_mfma_f32_16x16x32_bf16 v[36:39], v[160:163], v[190:193], v[36:39]
	v_mfma_f32_16x16x32_bf16 v[32:35], v[168:171], v[190:193], v[32:35]
	v_mfma_f32_16x16x32_bf16 v[20:23], v[160:163], v[198:201], v[20:23]
	v_mfma_f32_16x16x32_bf16 v[16:19], v[168:171], v[198:201], v[16:19]
	v_mfma_f32_16x16x32_bf16 v[4:7], v[160:163], v[220:223], v[4:7]
	v_mfma_f32_16x16x32_bf16 v[0:3], v[168:171], v[220:223], v[0:3]
	s_setprio 0
	s_add_i32 s67, s67, 2
	s_add_u32 s52, s52, 0x100
	s_addc_u32 s53, s53, 0
	s_add_u32 s65, s65, 0x100
	s_addc_u32 s66, s66, 0
	s_add_u32 s6, s52, 0xfffc0080
	s_addc_u32 s20, s53, -1
	s_cmp_eq_u32 s67, 12
	s_cselect_b32 s57, s33, s20
	s_cselect_b32 s56, s39, s6
	s_cselect_b32 s55, s43, s66
	s_cselect_b32 s54, s45, s65
	s_cmp_gt_u32 s67, 13
	s_barrier
	s_cbranch_scc0 .LBB0_1411
	s_and_b64 vcc, exec, s[40:41]
	s_cbranch_vccz .LBB0_1414
	s_barrier

.LBB0_1977:
	s_add_u32 s66, s50, 0x100
	v_mov_b32_e32 v0, 0
	s_addc_u32 s67, s51, 0
	s_mov_b32 s68, -2
	v_mov_b32_e32 v1, v0
	v_mov_b32_e32 v2, v0
	v_mov_b32_e32 v3, v0
	v_mov_b32_e32 v4, v0
	v_mov_b32_e32 v5, v0
	v_mov_b32_e32 v6, v0
	v_mov_b32_e32 v7, v0
	v_mov_b32_e32 v16, v0
	v_mov_b32_e32 v17, v0
	v_mov_b32_e32 v18, v0
	v_mov_b32_e32 v19, v0
	v_mov_b32_e32 v20, v0
	v_mov_b32_e32 v21, v0
	v_mov_b32_e32 v22, v0
	v_mov_b32_e32 v23, v0
	v_mov_b32_e32 v32, v0
	v_mov_b32_e32 v33, v0
	v_mov_b32_e32 v34, v0
	v_mov_b32_e32 v35, v0
	v_mov_b32_e32 v36, v0
	v_mov_b32_e32 v37, v0
	v_mov_b32_e32 v38, v0
	v_mov_b32_e32 v39, v0
	v_mov_b32_e32 v50, v0
	v_mov_b32_e32 v51, v0
	v_mov_b32_e32 v52, v0
	v_mov_b32_e32 v53, v0
	v_mov_b32_e32 v54, v0
	v_mov_b32_e32 v55, v0
	v_mov_b32_e32 v56, v0
	v_mov_b32_e32 v57, v0
	v_mov_b32_e32 v8, v0
	v_mov_b32_e32 v9, v0
	v_mov_b32_e32 v10, v0
	v_mov_b32_e32 v11, v0
	v_mov_b32_e32 v12, v0
	v_mov_b32_e32 v13, v0
	v_mov_b32_e32 v14, v0
	v_mov_b32_e32 v15, v0
	v_mov_b32_e32 v24, v0
	v_mov_b32_e32 v25, v0
	v_mov_b32_e32 v26, v0
	v_mov_b32_e32 v27, v0
	v_mov_b32_e32 v28, v0
	v_mov_b32_e32 v29, v0
	v_mov_b32_e32 v30, v0
	v_mov_b32_e32 v31, v0
	v_mov_b32_e32 v40, v0
	v_mov_b32_e32 v41, v0
	v_mov_b32_e32 v42, v0
	v_mov_b32_e32 v43, v0
	v_mov_b32_e32 v44, v0
	v_mov_b32_e32 v45, v0
	v_mov_b32_e32 v46, v0
	v_mov_b32_e32 v47, v0
	v_mov_b32_e32 v58, v0
	v_mov_b32_e32 v59, v0
	v_mov_b32_e32 v60, v0
	v_mov_b32_e32 v61, v0
	v_mov_b32_e32 v62, v0
	v_mov_b32_e32 v63, v0
	v_mov_b32_e32 v64, v0
	v_mov_b32_e32 v65, v0
	v_mov_b32_e32 v66, v0
	v_mov_b32_e32 v67, v0
	v_mov_b32_e32 v68, v0
	v_mov_b32_e32 v69, v0
	v_mov_b32_e32 v70, v0
	v_mov_b32_e32 v71, v0
	v_mov_b32_e32 v72, v0
	v_mov_b32_e32 v73, v0
	v_mov_b32_e32 v82, v0
	v_mov_b32_e32 v83, v0
	v_mov_b32_e32 v84, v0
	v_mov_b32_e32 v85, v0
	v_mov_b32_e32 v86, v0
	v_mov_b32_e32 v87, v0
	v_mov_b32_e32 v88, v0
	v_mov_b32_e32 v89, v0
	v_mov_b32_e32 v98, v0
	v_mov_b32_e32 v99, v0
	v_mov_b32_e32 v100, v0
	v_mov_b32_e32 v101, v0
	v_mov_b32_e32 v102, v0
	v_mov_b32_e32 v103, v0
	v_mov_b32_e32 v104, v0
	v_mov_b32_e32 v105, v0
	v_mov_b32_e32 v114, v0
	v_mov_b32_e32 v115, v0
	v_mov_b32_e32 v116, v0
	v_mov_b32_e32 v117, v0
	v_mov_b32_e32 v118, v0
	v_mov_b32_e32 v119, v0
	v_mov_b32_e32 v120, v0
	v_mov_b32_e32 v121, v0
	v_mov_b32_e32 v74, v0
	v_mov_b32_e32 v75, v0
	v_mov_b32_e32 v76, v0
	v_mov_b32_e32 v77, v0
	v_mov_b32_e32 v78, v0
	v_mov_b32_e32 v79, v0
	v_mov_b32_e32 v80, v0
	v_mov_b32_e32 v81, v0
	v_mov_b32_e32 v90, v0
	v_mov_b32_e32 v91, v0
	v_mov_b32_e32 v92, v0
	v_mov_b32_e32 v93, v0
	v_mov_b32_e32 v94, v0
	v_mov_b32_e32 v95, v0
	v_mov_b32_e32 v96, v0
	v_mov_b32_e32 v97, v0
	v_mov_b32_e32 v106, v0
	v_mov_b32_e32 v107, v0
	v_mov_b32_e32 v108, v0
	v_mov_b32_e32 v109, v0
	v_mov_b32_e32 v110, v0
	v_mov_b32_e32 v111, v0
	v_mov_b32_e32 v112, v0
	v_mov_b32_e32 v113, v0
	v_mov_b32_e32 v126, v0
	v_mov_b32_e32 v127, v0
	v_mov_b32_e32 v128, v0
	v_mov_b32_e32 v129, v0
	v_mov_b32_e32 v134, v0
	v_mov_b32_e32 v135, v0
	v_mov_b32_e32 v136, v0
	v_mov_b32_e32 v137, v0
	s_add_u32 s50, s48, 0x100
	s_addc_u32 s51, s49, 0
	s_cmp_eq_u32 s68, 40
	s_cselect_b32 s55, s45, s51
	s_cselect_b32 s54, s44, s50
	s_cselect_b32 s53, s47, s67
	s_cselect_b32 s52, s46, s66
.LBB0_1978:
	s_add_i32 s6, 0, 0x10000
	v_add_u32_e32 v48, s6, v183
	s_add_i32 s26, 0, 0x14000
	ds_read_b128 v[122:125], v48
	ds_read_b128 v[130:133], v48 offset:1024
	ds_read_b128 v[138:141], v48 offset:2048
	ds_read_b128 v[142:145], v48 offset:3072
	v_add_u32_e32 v48, s26, v183
	ds_read_b128 v[146:149], v48
	ds_read_b128 v[150:153], v48 offset:1024
	ds_read_b128 v[168:171], v48 offset:2048
	ds_read_b128 v[172:175], v48 offset:3072
	v_lshl_add_u64 v[180:181], s[48:49], 0, v[164:165]
	s_add_i32 m0, s56, 0xc000
	ds_read_b128 v[176:179], v185
	ds_read_b128 v[186:189], v185 offset:1024
	ds_read_b128 v[190:193], v185 offset:2048
	ds_read_b128 v[194:197], v185 offset:3072
	ds_read_b128 v[198:201], v185 offset:4096
	ds_read_b128 v[216:219], v185 offset:5120
	ds_read_b128 v[220:223], v185 offset:6144
	ds_read_b128 v[224:227], v185 offset:7168
	global_load_lds_dwordx4 v[180:181], off
	v_lshl_add_u64 v[180:181], s[48:49], 0, v[166:167]
	s_add_i32 m0, s56, 0xe000
	s_nop 0
	global_load_lds_dwordx4 v[180:181], off
	s_waitcnt vmcnt(8)
	s_waitcnt lgkmcnt(0)
	s_barrier
	s_setprio 1
	v_mfma_f32_16x16x32_bf16 v[134:137], v[122:125], v[176:179], v[134:137]
	v_mfma_f32_16x16x32_bf16 v[126:129], v[138:141], v[176:179], v[126:129]
	v_mfma_f32_16x16x32_bf16 v[110:113], v[122:125], v[190:193], v[110:113]
	v_mfma_f32_16x16x32_bf16 v[106:109], v[138:141], v[190:193], v[106:109]
	v_mfma_f32_16x16x32_bf16 v[94:97], v[122:125], v[198:201], v[94:97]
	v_mfma_f32_16x16x32_bf16 v[90:93], v[138:141], v[198:201], v[90:93]
	v_mfma_f32_16x16x32_bf16 v[78:81], v[122:125], v[220:223], v[78:81]
	v_mfma_f32_16x16x32_bf16 v[74:77], v[138:141], v[220:223], v[74:77]
	v_mfma_f32_16x16x32_bf16 v[134:137], v[130:133], v[186:189], v[134:137]
	v_mfma_f32_16x16x32_bf16 v[126:129], v[142:145], v[186:189], v[126:129]
	v_mfma_f32_16x16x32_bf16 v[110:113], v[130:133], v[194:197], v[110:113]
	v_mfma_f32_16x16x32_bf16 v[106:109], v[142:145], v[194:197], v[106:109]
	v_mfma_f32_16x16x32_bf16 v[94:97], v[130:133], v[216:219], v[94:97]
	v_mfma_f32_16x16x32_bf16 v[90:93], v[142:145], v[216:219], v[90:93]
	v_mfma_f32_16x16x32_bf16 v[78:81], v[130:133], v[224:227], v[78:81]
	v_mfma_f32_16x16x32_bf16 v[74:77], v[142:145], v[224:227], v[74:77]
	v_mfma_f32_16x16x32_bf16 v[118:121], v[146:149], v[176:179], v[118:121]
	v_mfma_f32_16x16x32_bf16 v[114:117], v[168:171], v[176:179], v[114:117]
	v_mfma_f32_16x16x32_bf16 v[102:105], v[146:149], v[190:193], v[102:105]
	v_mfma_f32_16x16x32_bf16 v[98:101], v[168:171], v[190:193], v[98:101]
	v_mfma_f32_16x16x32_bf16 v[86:89], v[146:149], v[198:201], v[86:89]
	v_mfma_f32_16x16x32_bf16 v[82:85], v[168:171], v[198:201], v[82:85]
	v_mfma_f32_16x16x32_bf16 v[70:73], v[146:149], v[220:223], v[70:73]
	v_mfma_f32_16x16x32_bf16 v[66:69], v[168:171], v[220:223], v[66:69]
	v_mfma_f32_16x16x32_bf16 v[118:121], v[150:153], v[186:189], v[118:121]
	v_mfma_f32_16x16x32_bf16 v[114:117], v[172:175], v[186:189], v[114:117]
	v_mfma_f32_16x16x32_bf16 v[102:105], v[150:153], v[194:197], v[102:105]
	v_mfma_f32_16x16x32_bf16 v[98:101], v[172:175], v[194:197], v[98:101]
	v_mfma_f32_16x16x32_bf16 v[86:89], v[150:153], v[216:219], v[86:89]
	v_mfma_f32_16x16x32_bf16 v[82:85], v[172:175], v[216:219], v[82:85]
	v_mfma_f32_16x16x32_bf16 v[70:73], v[150:153], v[224:227], v[70:73]
	v_mfma_f32_16x16x32_bf16 v[66:69], v[172:175], v[224:227], v[66:69]
	s_setprio 0
	s_barrier
	s_add_i32 s6, s6, s24
	v_lshl_add_u64 v[180:181], s[52:53], 0, v[158:159]
	s_mov_b32 m0, s6
	ds_read_b128 v[176:179], v185 offset:16384
	ds_read_b128 v[186:189], v185 offset:17408
	ds_read_b128 v[190:193], v185 offset:18432
	ds_read_b128 v[194:197], v185 offset:19456
	ds_read_b128 v[198:201], v185 offset:20480
	ds_read_b128 v[216:219], v185 offset:21504
	ds_read_b128 v[220:223], v185 offset:22528
	ds_read_b128 v[224:227], v185 offset:23552
	global_load_lds_dwordx4 v[180:181], off
	s_add_i32 m0, s6, 0x2000
	s_add_u32 s20, s52, 0xb0000
	v_lshl_add_u64 v[202:203], s[52:53], 0, v[162:163]
	s_addc_u32 s21, s53, 0
	s_add_i32 s6, s26, s24
	global_load_lds_dwordx4 v[202:203], off
	v_lshl_add_u64 v[212:213], s[20:21], 0, v[158:159]
	s_mov_b32 m0, s6
	v_lshl_add_u64 v[214:215], s[54:55], 0, v[160:161]
	global_load_lds_dwordx4 v[212:213], off
	v_lshl_add_u64 v[212:213], s[20:21], 0, v[162:163]
	s_add_i32 m0, s6, 0x2000
	s_nop 0
	global_load_lds_dwordx4 v[212:213], off
	v_lshl_add_u64 v[212:213], s[54:55], 0, v[156:157]
	s_mov_b32 m0, s56
	s_nop 0
	global_load_lds_dwordx4 v[212:213], off
	s_mov_b32 m0, s57
	s_nop 0
	global_load_lds_dwordx4 v[214:215], off
	s_waitcnt vmcnt(8)
	s_waitcnt lgkmcnt(0)
	s_barrier
	s_setprio 1
	v_mfma_f32_16x16x32_bf16 v[62:65], v[122:125], v[176:179], v[62:65]
	v_mfma_f32_16x16x32_bf16 v[58:61], v[138:141], v[176:179], v[58:61]
	v_mfma_f32_16x16x32_bf16 v[44:47], v[122:125], v[190:193], v[44:47]
	v_mfma_f32_16x16x32_bf16 v[40:43], v[138:141], v[190:193], v[40:43]
	v_mfma_f32_16x16x32_bf16 v[28:31], v[122:125], v[198:201], v[28:31]
	v_mfma_f32_16x16x32_bf16 v[24:27], v[138:141], v[198:201], v[24:27]
	v_mfma_f32_16x16x32_bf16 v[12:15], v[122:125], v[220:223], v[12:15]
	v_mfma_f32_16x16x32_bf16 v[8:11], v[138:141], v[220:223], v[8:11]
	v_mfma_f32_16x16x32_bf16 v[62:65], v[130:133], v[186:189], v[62:65]
	v_mfma_f32_16x16x32_bf16 v[58:61], v[142:145], v[186:189], v[58:61]
	v_mfma_f32_16x16x32_bf16 v[44:47], v[130:133], v[194:197], v[44:47]
	v_mfma_f32_16x16x32_bf16 v[40:43], v[142:145], v[194:197], v[40:43]
	v_mfma_f32_16x16x32_bf16 v[28:31], v[130:133], v[216:219], v[28:31]
	v_mfma_f32_16x16x32_bf16 v[24:27], v[142:145], v[216:219], v[24:27]
	v_mfma_f32_16x16x32_bf16 v[12:15], v[130:133], v[224:227], v[12:15]
	v_mfma_f32_16x16x32_bf16 v[8:11], v[142:145], v[224:227], v[8:11]
	v_mfma_f32_16x16x32_bf16 v[54:57], v[146:149], v[176:179], v[54:57]
	v_mfma_f32_16x16x32_bf16 v[50:53], v[168:171], v[176:179], v[50:53]
	v_mfma_f32_16x16x32_bf16 v[36:39], v[146:149], v[190:193], v[36:39]
	v_mfma_f32_16x16x32_bf16 v[32:35], v[168:171], v[190:193], v[32:35]
	v_mfma_f32_16x16x32_bf16 v[20:23], v[146:149], v[198:201], v[20:23]
	v_mfma_f32_16x16x32_bf16 v[16:19], v[168:171], v[198:201], v[16:19]
	v_mfma_f32_16x16x32_bf16 v[4:7], v[146:149], v[220:223], v[4:7]
	v_mfma_f32_16x16x32_bf16 v[0:3], v[168:171], v[220:223], v[0:3]
	v_mfma_f32_16x16x32_bf16 v[54:57], v[150:153], v[186:189], v[54:57]
	v_mfma_f32_16x16x32_bf16 v[50:53], v[172:175], v[186:189], v[50:53]
	v_mfma_f32_16x16x32_bf16 v[36:39], v[150:153], v[194:197], v[36:39]
	v_mfma_f32_16x16x32_bf16 v[32:35], v[172:175], v[194:197], v[32:35]
	v_mfma_f32_16x16x32_bf16 v[20:23], v[150:153], v[216:219], v[20:23]
	v_mfma_f32_16x16x32_bf16 v[16:19], v[172:175], v[216:219], v[16:19]
	v_mfma_f32_16x16x32_bf16 v[4:7], v[150:153], v[224:227], v[4:7]
	v_mfma_f32_16x16x32_bf16 v[0:3], v[172:175], v[224:227], v[0:3]
	s_setprio 0
	s_barrier
	s_add_i32 s6, 0, 0x18000
	v_add_u32_e32 v48, s6, v183
	s_add_i32 s26, 0, 0x1c000
	ds_read_b128 v[122:125], v48
	ds_read_b128 v[130:133], v48 offset:1024
	ds_read_b128 v[138:141], v48 offset:2048
	ds_read_b128 v[142:145], v48 offset:3072
	v_add_u32_e32 v48, s26, v183
	ds_read_b128 v[146:149], v48
	ds_read_b128 v[150:153], v48 offset:1024
	ds_read_b128 v[168:171], v48 offset:2048
	ds_read_b128 v[172:175], v48 offset:3072
	s_add_u32 s20, s54, 0xb0000
	s_addc_u32 s21, s55, 0
	s_mov_b32 m0, s58
	v_lshl_add_u64 v[228:229], s[20:21], 0, v[156:157]
	ds_read_b128 v[176:179], v185 offset:32768
	ds_read_b128 v[186:189], v185 offset:33792
	ds_read_b128 v[190:193], v185 offset:34816
	ds_read_b128 v[194:197], v185 offset:35840
	ds_read_b128 v[198:201], v185 offset:36864
	ds_read_b128 v[216:219], v185 offset:37888
	ds_read_b128 v[220:223], v185 offset:38912
	ds_read_b128 v[224:227], v185 offset:39936
	global_load_lds_dwordx4 v[228:229], off
	v_lshl_add_u64 v[228:229], s[20:21], 0, v[160:161]
	s_mov_b32 m0, s59
	s_nop 0
	global_load_lds_dwordx4 v[228:229], off
	s_waitcnt vmcnt(8)
	s_waitcnt lgkmcnt(0)
	s_barrier
	s_setprio 1
	v_mfma_f32_16x16x32_bf16 v[134:137], v[122:125], v[176:179], v[134:137]
	v_mfma_f32_16x16x32_bf16 v[126:129], v[138:141], v[176:179], v[126:129]
	v_mfma_f32_16x16x32_bf16 v[110:113], v[122:125], v[190:193], v[110:113]
	v_mfma_f32_16x16x32_bf16 v[106:109], v[138:141], v[190:193], v[106:109]
	v_mfma_f32_16x16x32_bf16 v[94:97], v[122:125], v[198:201], v[94:97]
	v_mfma_f32_16x16x32_bf16 v[90:93], v[138:141], v[198:201], v[90:93]
	v_mfma_f32_16x16x32_bf16 v[78:81], v[122:125], v[220:223], v[78:81]
	v_mfma_f32_16x16x32_bf16 v[74:77], v[138:141], v[220:223], v[74:77]
	v_mfma_f32_16x16x32_bf16 v[134:137], v[130:133], v[186:189], v[134:137]
	v_mfma_f32_16x16x32_bf16 v[126:129], v[142:145], v[186:189], v[126:129]
	v_mfma_f32_16x16x32_bf16 v[110:113], v[130:133], v[194:197], v[110:113]
	v_mfma_f32_16x16x32_bf16 v[106:109], v[142:145], v[194:197], v[106:109]
	v_mfma_f32_16x16x32_bf16 v[94:97], v[130:133], v[216:219], v[94:97]
	v_mfma_f32_16x16x32_bf16 v[90:93], v[142:145], v[216:219], v[90:93]
	v_mfma_f32_16x16x32_bf16 v[78:81], v[130:133], v[224:227], v[78:81]
	v_mfma_f32_16x16x32_bf16 v[74:77], v[142:145], v[224:227], v[74:77]
	v_mfma_f32_16x16x32_bf16 v[118:121], v[146:149], v[176:179], v[118:121]
	v_mfma_f32_16x16x32_bf16 v[114:117], v[168:171], v[176:179], v[114:117]
	v_mfma_f32_16x16x32_bf16 v[102:105], v[146:149], v[190:193], v[102:105]
	v_mfma_f32_16x16x32_bf16 v[98:101], v[168:171], v[190:193], v[98:101]
	v_mfma_f32_16x16x32_bf16 v[86:89], v[146:149], v[198:201], v[86:89]
	v_mfma_f32_16x16x32_bf16 v[82:85], v[168:171], v[198:201], v[82:85]
	v_mfma_f32_16x16x32_bf16 v[70:73], v[146:149], v[220:223], v[70:73]
	v_mfma_f32_16x16x32_bf16 v[66:69], v[168:171], v[220:223], v[66:69]
	v_mfma_f32_16x16x32_bf16 v[118:121], v[150:153], v[186:189], v[118:121]
	v_mfma_f32_16x16x32_bf16 v[114:117], v[172:175], v[186:189], v[114:117]
	v_mfma_f32_16x16x32_bf16 v[102:105], v[150:153], v[194:197], v[102:105]
	v_mfma_f32_16x16x32_bf16 v[98:101], v[172:175], v[194:197], v[98:101]
	v_mfma_f32_16x16x32_bf16 v[86:89], v[150:153], v[216:219], v[86:89]
	v_mfma_f32_16x16x32_bf16 v[82:85], v[172:175], v[216:219], v[82:85]
	v_mfma_f32_16x16x32_bf16 v[70:73], v[150:153], v[224:227], v[70:73]
	v_mfma_f32_16x16x32_bf16 v[66:69], v[172:175], v[224:227], v[66:69]
	s_setprio 0
	s_barrier
	s_add_i32 s6, s6, s24
	v_lshl_add_u64 v[180:181], v[180:181], 0, s[30:31]
	s_mov_b32 m0, s6
	ds_read_b128 v[176:179], v185 offset:49152
	ds_read_b128 v[186:189], v185 offset:50176
	ds_read_b128 v[190:193], v185 offset:51200
	ds_read_b128 v[194:197], v185 offset:52224
	ds_read_b128 v[198:201], v185 offset:53248
	ds_read_b128 v[216:219], v185 offset:54272
	ds_read_b128 v[220:223], v185 offset:55296
	ds_read_b128 v[224:227], v185 offset:56320
	global_load_lds_dwordx4 v[180:181], off
	s_add_i32 m0, s6, 0x2000
	s_add_u32 s20, s52, 0xb0080
	v_lshl_add_u64 v[180:181], v[202:203], 0, s[30:31]
	s_addc_u32 s21, s53, 0
	s_add_i32 s6, s26, s24
	global_load_lds_dwordx4 v[180:181], off
	v_lshl_add_u64 v[180:181], s[20:21], 0, v[158:159]
	s_mov_b32 m0, s6
	s_nop 0
	global_load_lds_dwordx4 v[180:181], off
	v_lshl_add_u64 v[180:181], s[20:21], 0, v[162:163]
	s_add_i32 m0, s6, 0x2000
	s_nop 0
	global_load_lds_dwordx4 v[180:181], off
	v_lshl_add_u64 v[180:181], v[212:213], 0, s[30:31]
	s_mov_b32 m0, s60
	s_nop 0
	global_load_lds_dwordx4 v[180:181], off
	v_lshl_add_u64 v[180:181], v[214:215], 0, s[30:31]
	s_mov_b32 m0, s61
	s_nop 0
	global_load_lds_dwordx4 v[180:181], off
	s_waitcnt vmcnt(8)
	s_waitcnt lgkmcnt(0)
	s_barrier
	s_setprio 1
	v_mfma_f32_16x16x32_bf16 v[62:65], v[122:125], v[176:179], v[62:65]
	v_mfma_f32_16x16x32_bf16 v[58:61], v[138:141], v[176:179], v[58:61]
	v_mfma_f32_16x16x32_bf16 v[44:47], v[122:125], v[190:193], v[44:47]
	v_mfma_f32_16x16x32_bf16 v[40:43], v[138:141], v[190:193], v[40:43]
	v_mfma_f32_16x16x32_bf16 v[28:31], v[122:125], v[198:201], v[28:31]
	v_mfma_f32_16x16x32_bf16 v[24:27], v[138:141], v[198:201], v[24:27]
	v_mfma_f32_16x16x32_bf16 v[12:15], v[122:125], v[220:223], v[12:15]
	v_mfma_f32_16x16x32_bf16 v[8:11], v[138:141], v[220:223], v[8:11]
	v_mfma_f32_16x16x32_bf16 v[62:65], v[130:133], v[186:189], v[62:65]
	v_mfma_f32_16x16x32_bf16 v[58:61], v[142:145], v[186:189], v[58:61]
	v_mfma_f32_16x16x32_bf16 v[44:47], v[130:133], v[194:197], v[44:47]
	v_mfma_f32_16x16x32_bf16 v[40:43], v[142:145], v[194:197], v[40:43]
	v_mfma_f32_16x16x32_bf16 v[28:31], v[130:133], v[216:219], v[28:31]
	v_mfma_f32_16x16x32_bf16 v[24:27], v[142:145], v[216:219], v[24:27]
	v_mfma_f32_16x16x32_bf16 v[12:15], v[130:133], v[224:227], v[12:15]
	v_mfma_f32_16x16x32_bf16 v[8:11], v[142:145], v[224:227], v[8:11]
	v_mfma_f32_16x16x32_bf16 v[54:57], v[146:149], v[176:179], v[54:57]
	v_mfma_f32_16x16x32_bf16 v[50:53], v[168:171], v[176:179], v[50:53]
	v_mfma_f32_16x16x32_bf16 v[36:39], v[146:149], v[190:193], v[36:39]
	v_mfma_f32_16x16x32_bf16 v[32:35], v[168:171], v[190:193], v[32:35]
	v_mfma_f32_16x16x32_bf16 v[20:23], v[146:149], v[198:201], v[20:23]
	v_mfma_f32_16x16x32_bf16 v[16:19], v[168:171], v[198:201], v[16:19]
	v_mfma_f32_16x16x32_bf16 v[4:7], v[146:149], v[220:223], v[4:7]
	v_mfma_f32_16x16x32_bf16 v[0:3], v[168:171], v[220:223], v[0:3]
	v_mfma_f32_16x16x32_bf16 v[54:57], v[150:153], v[186:189], v[54:57]
	v_mfma_f32_16x16x32_bf16 v[50:53], v[172:175], v[186:189], v[50:53]
	v_mfma_f32_16x16x32_bf16 v[36:39], v[150:153], v[194:197], v[36:39]
	v_mfma_f32_16x16x32_bf16 v[32:35], v[172:175], v[194:197], v[32:35]
	v_mfma_f32_16x16x32_bf16 v[20:23], v[150:153], v[216:219], v[20:23]
	v_mfma_f32_16x16x32_bf16 v[16:19], v[172:175], v[216:219], v[16:19]
	v_mfma_f32_16x16x32_bf16 v[4:7], v[150:153], v[224:227], v[4:7]
	v_mfma_f32_16x16x32_bf16 v[0:3], v[172:175], v[224:227], v[0:3]
	s_setprio 0
	s_add_i32 s68, s68, 2
	s_add_u32 s66, s66, 0x100
	s_addc_u32 s67, s67, 0
	s_mov_b64 s[48:49], s[50:51]
	s_add_u32 s50, s48, 0x100
	s_addc_u32 s51, s49, 0
	s_cmp_eq_u32 s68, 40
	s_cselect_b32 s55, s45, s51
	s_cselect_b32 s54, s44, s50
	s_cselect_b32 s53, s47, s67
	s_cselect_b32 s52, s46, s66
	s_cmp_gt_u32 s68, 41
	s_barrier
	s_cbranch_scc0 .LBB0_1978
	s_and_b64 vcc, exec, s[42:43]
	s_cbranch_vccz .LBB0_1981
	s_barrier
